# DPP: retention unit per-head norm xor-shuffle sums by v_mov_dpp / permlane16_swap instead of 80 ds_bpermute round trips per unit
# baseline (speedup 1.0000x reference)
; DI void ret_unit(LAS unsigned char* lds, bf16_t* MX, const bf16_t* VT, bf16_t* ST, int b, int hh, int qt, float lgf, float nlgb, int wave, const int mode) {
;     ...
;     for (int i = 0; i < 16; ++i) {
;         float ss = 0.f;
; #pragma unroll
;         for (int db = 0; db < 8; ++db) ss += z[db][i] * z[db][i];
;         ss += shx(ss, 1); ss += shx(ss, 2); ss += shx(ss, 4); ss += shx(ss, 8); ss += shx(ss, 16);
;         nrm[i] = 1.0f / sqrtf(ss * (1.0f / 256.0f) + EPS);
;     }
.LBB0_154:
	v_mul_f32_e32 v128, v96, v96
	v_fmac_f32_e32 v128, v112, v112
	v_fmac_f32_e32 v128, v80, v80
	v_fmac_f32_e32 v128, v64, v64
	v_fmac_f32_e32 v128, v48, v48
	v_mbcnt_lo_u32_b32 v137, -1, 0
	v_mbcnt_hi_u32_b32 v137, -1, v137
	v_fmac_f32_e32 v128, v32, v32
	v_mbcnt_lo_u32_b32 v129, -1, 0
	v_mbcnt_hi_u32_b32 v129, -1, v129
	v_fmac_f32_e32 v128, v16, v16
	v_lshlrev_b32_e32 v129, 2, v129
	v_fmac_f32_e32 v128, v0, v0
	v_xor_b32_e32 v129, 4, v129
	s_nop 1
	v_mov_b32_dpp v129, v128 quad_perm:[1,0,3,2] row_mask:0xf bank_mask:0xf
	s_mov_b32 s11, 0xf800000
	s_waitcnt lgkmcnt(0)
	v_add_f32_e32 v128, v128, v129
	v_mbcnt_lo_u32_b32 v129, -1, 0
	v_mbcnt_hi_u32_b32 v129, -1, v129
	s_nop 0
	v_lshlrev_b32_e32 v129, 2, v129
	v_xor_b32_e32 v129, 8, v129
	s_nop 1
	v_mov_b32_dpp v129, v128 quad_perm:[2,3,0,1] row_mask:0xf bank_mask:0xf
	s_waitcnt lgkmcnt(0)
	v_add_f32_e32 v128, v128, v129
	v_mbcnt_lo_u32_b32 v129, -1, 0
	v_mbcnt_hi_u32_b32 v129, -1, v129
	s_nop 0
	v_lshlrev_b32_e32 v129, 2, v129
	v_xor_b32_e32 v129, 16, v129
	s_nop 1
	v_mov_b32_dpp v129, v128 row_half_mirror row_mask:0xf bank_mask:0xf
	s_waitcnt lgkmcnt(0)
	v_add_f32_e32 v128, v128, v129
	v_mbcnt_lo_u32_b32 v129, -1, 0
	v_mbcnt_hi_u32_b32 v129, -1, v129
	s_nop 0
	v_lshlrev_b32_e32 v129, 2, v129
	v_xor_b32_e32 v129, 32, v129
	s_nop 1
	v_mov_b32_dpp v129, v128 row_ror:8 row_mask:0xf bank_mask:0xf
	s_waitcnt lgkmcnt(0)
	v_add_f32_e32 v128, v128, v129
	v_mbcnt_lo_u32_b32 v129, -1, 0
	v_mbcnt_hi_u32_b32 v129, -1, v129
	s_nop 0
	v_lshlrev_b32_e32 v129, 2, v129
	v_xor_b32_e32 v129, 64, v129
	v_mov_b32_e32 v129, v128
	s_nop 1
	v_permlane16_swap_b32_e32 v128, v129
	s_waitcnt lgkmcnt(0)
	v_add_f32_e32 v128, v128, v129
	v_fmamk_f32 v128, v128, 0x3b800000, v237
	v_cmp_gt_f32_e32 vcc, s11, v128
	v_mul_f32_e32 v129, 0x4f800000, v128
	s_nop 0
	v_cndmask_b32_e32 v128, v128, v129, vcc
	v_sqrt_f32_e32 v129, v128
	s_nop 0
	v_add_u32_e32 v130, -1, v129
	v_fma_f32 v131, -v130, v129, v128
	v_cmp_ge_f32_e64 s[4:5], 0, v131
	v_add_u32_e32 v131, 1, v129
	s_nop 0
	v_cndmask_b32_e64 v130, v129, v130, s[4:5]
	v_fma_f32 v129, -v131, v129, v128
	v_cmp_lt_f32_e64 s[4:5], 0, v129
	s_nop 1
	v_cndmask_b32_e64 v129, v130, v131, s[4:5]
	v_mul_f32_e32 v130, 0x37800000, v129
	v_cndmask_b32_e32 v129, v129, v130, vcc
	v_cmp_class_f32_e32 vcc, v128, v238
	s_nop 1
	v_cndmask_b32_e32 v128, v129, v128, vcc
	v_div_scale_f32 v129, s[4:5], v128, v128, 1.0
	v_rcp_f32_e32 v130, v129
	s_nop 0
	v_fma_f32 v131, -v129, v130, 1.0
	v_fmac_f32_e32 v130, v131, v130
	v_div_scale_f32 v131, vcc, 1.0, v128, 1.0
	v_mul_f32_e32 v132, v131, v130
	v_fma_f32 v133, -v129, v132, v131
	v_fmac_f32_e32 v132, v133, v130
	v_fma_f32 v129, -v129, v132, v131
	v_div_fmas_f32 v129, v129, v130, v132
	v_div_fixup_f32 v128, v129, v128, 1.0
	v_mul_f32_e32 v129, v97, v97
	v_fmac_f32_e32 v129, v113, v113
	v_fmac_f32_e32 v129, v81, v81
	v_fmac_f32_e32 v129, v65, v65
	v_fmac_f32_e32 v129, v49, v49
	v_fmac_f32_e32 v129, v33, v33
	v_mbcnt_lo_u32_b32 v130, -1, 0
	v_mbcnt_hi_u32_b32 v130, -1, v130
	v_fmac_f32_e32 v129, v17, v17
	v_lshlrev_b32_e32 v130, 2, v130
	v_fmac_f32_e32 v129, v1, v1
	v_xor_b32_e32 v130, 4, v130
	s_nop 1
	v_mov_b32_dpp v130, v129 quad_perm:[1,0,3,2] row_mask:0xf bank_mask:0xf
	v_mul_f32_e32 v112, v112, v128
	v_mul_f32_e32 v96, v96, v128
	v_mul_f32_e32 v80, v80, v128
	v_mul_f32_e32 v64, v64, v128
	s_waitcnt lgkmcnt(0)
	v_add_f32_e32 v129, v129, v130
	v_mbcnt_lo_u32_b32 v130, -1, 0
	v_mbcnt_hi_u32_b32 v130, -1, v130
	v_mul_f32_e32 v48, v48, v128
	v_lshlrev_b32_e32 v130, 2, v130
	v_xor_b32_e32 v130, 8, v130
	s_nop 1
	v_mov_b32_dpp v130, v129 quad_perm:[2,3,0,1] row_mask:0xf bank_mask:0xf
	v_mul_f32_e32 v32, v32, v128
	v_mul_f32_e32 v16, v16, v128
	v_mul_f32_e32 v0, v0, v128
	s_waitcnt lgkmcnt(0)
	v_add_f32_e32 v129, v129, v130
	v_mbcnt_lo_u32_b32 v130, -1, 0
	v_mbcnt_hi_u32_b32 v130, -1, v130
	s_nop 0
	v_lshlrev_b32_e32 v130, 2, v130
	v_xor_b32_e32 v130, 16, v130
	s_nop 1
	v_mov_b32_dpp v130, v129 row_half_mirror row_mask:0xf bank_mask:0xf
	s_waitcnt lgkmcnt(0)
	v_add_f32_e32 v129, v129, v130
	v_mbcnt_lo_u32_b32 v130, -1, 0
	v_mbcnt_hi_u32_b32 v130, -1, v130
	s_nop 0
	v_lshlrev_b32_e32 v130, 2, v130
	v_xor_b32_e32 v130, 32, v130
	s_nop 1
	v_mov_b32_dpp v130, v129 row_ror:8 row_mask:0xf bank_mask:0xf
	s_waitcnt lgkmcnt(0)
	v_add_f32_e32 v129, v129, v130
	v_mbcnt_lo_u32_b32 v130, -1, 0
	v_mbcnt_hi_u32_b32 v130, -1, v130
	s_nop 0
	v_lshlrev_b32_e32 v130, 2, v130
	v_xor_b32_e32 v130, 64, v130
	v_mov_b32_e32 v130, v129
	s_nop 1
	v_permlane16_swap_b32_e32 v129, v130
	s_waitcnt lgkmcnt(0)
	v_add_f32_e32 v129, v129, v130
	v_fmamk_f32 v129, v129, 0x3b800000, v237
	v_cmp_gt_f32_e32 vcc, s11, v129
	v_mul_f32_e32 v130, 0x4f800000, v129
	s_nop 0
	v_cndmask_b32_e32 v129, v129, v130, vcc
	v_sqrt_f32_e32 v130, v129
	s_nop 0
	v_add_u32_e32 v131, -1, v130
	v_fma_f32 v132, -v131, v130, v129
	v_cmp_ge_f32_e64 s[4:5], 0, v132
	v_add_u32_e32 v132, 1, v130
	s_nop 0
	v_cndmask_b32_e64 v131, v130, v131, s[4:5]
	v_fma_f32 v130, -v132, v130, v129
	v_cmp_lt_f32_e64 s[4:5], 0, v130
	s_nop 1
	v_cndmask_b32_e64 v130, v131, v132, s[4:5]
	v_mul_f32_e32 v131, 0x37800000, v130
	v_cndmask_b32_e32 v130, v130, v131, vcc
	v_cmp_class_f32_e32 vcc, v129, v238
	s_nop 1
	v_cndmask_b32_e32 v129, v130, v129, vcc
	v_div_scale_f32 v130, s[4:5], v129, v129, 1.0
	v_rcp_f32_e32 v131, v130
	s_nop 0
	v_fma_f32 v132, -v130, v131, 1.0
	v_fmac_f32_e32 v131, v132, v131
	v_div_scale_f32 v132, vcc, 1.0, v129, 1.0
	v_mul_f32_e32 v133, v132, v131
	v_fma_f32 v134, -v130, v133, v132
	v_fmac_f32_e32 v133, v134, v131
	v_fma_f32 v130, -v130, v133, v132
	v_div_fmas_f32 v130, v130, v131, v133
	v_div_fixup_f32 v129, v130, v129, 1.0
	v_mul_f32_e32 v130, v98, v98
	v_fmac_f32_e32 v130, v114, v114
	v_fmac_f32_e32 v130, v82, v82
	v_fmac_f32_e32 v130, v66, v66
	v_fmac_f32_e32 v130, v50, v50
	v_fmac_f32_e32 v130, v34, v34
	v_mbcnt_lo_u32_b32 v131, -1, 0
	v_mbcnt_hi_u32_b32 v131, -1, v131
	v_fmac_f32_e32 v130, v18, v18
	v_lshlrev_b32_e32 v131, 2, v131
	v_fmac_f32_e32 v130, v2, v2
	v_xor_b32_e32 v131, 4, v131
	s_nop 1
	v_mov_b32_dpp v131, v130 quad_perm:[1,0,3,2] row_mask:0xf bank_mask:0xf
	s_waitcnt lgkmcnt(0)
; DI void ret_unit(LAS unsigned char* lds, bf16_t* MX, const bf16_t* VT, bf16_t* ST, int b, int hh, int qt, float lgf, float nlgb, int wave, const int mode) {
;     ...
;     for (int i = 0; i < 16; ++i) {
;         float ss = 0.f;
; #pragma unroll
;         for (int db = 0; db < 8; ++db) ss += z[db][i] * z[db][i];
;         ss += shx(ss, 1); ss += shx(ss, 2); ss += shx(ss, 4); ss += shx(ss, 8); ss += shx(ss, 16);
;         nrm[i] = 1.0f / sqrtf(ss * (1.0f / 256.0f) + EPS);
;     }
	v_add_f32_e32 v130, v130, v131
	v_mbcnt_lo_u32_b32 v131, -1, 0
	v_mbcnt_hi_u32_b32 v131, -1, v131
	s_nop 0
	v_lshlrev_b32_e32 v131, 2, v131
	v_xor_b32_e32 v131, 8, v131
	s_nop 1
	v_mov_b32_dpp v131, v130 quad_perm:[2,3,0,1] row_mask:0xf bank_mask:0xf
	s_waitcnt lgkmcnt(0)
	v_add_f32_e32 v130, v130, v131
	v_mbcnt_lo_u32_b32 v131, -1, 0
	v_mbcnt_hi_u32_b32 v131, -1, v131
	s_nop 0
	v_lshlrev_b32_e32 v131, 2, v131
	v_xor_b32_e32 v131, 16, v131
	s_nop 1
	v_mov_b32_dpp v131, v130 row_half_mirror row_mask:0xf bank_mask:0xf
	s_waitcnt lgkmcnt(0)
	v_add_f32_e32 v130, v130, v131
	v_mbcnt_lo_u32_b32 v131, -1, 0
	v_mbcnt_hi_u32_b32 v131, -1, v131
	s_nop 0
	v_lshlrev_b32_e32 v131, 2, v131
	v_xor_b32_e32 v131, 32, v131
	s_nop 1
	v_mov_b32_dpp v131, v130 row_ror:8 row_mask:0xf bank_mask:0xf
	s_waitcnt lgkmcnt(0)
	v_add_f32_e32 v130, v130, v131
	v_mbcnt_lo_u32_b32 v131, -1, 0
	v_mbcnt_hi_u32_b32 v131, -1, v131
	s_nop 0
	v_lshlrev_b32_e32 v131, 2, v131
	v_xor_b32_e32 v131, 64, v131
	v_mov_b32_e32 v131, v130
	s_nop 1
	v_permlane16_swap_b32_e32 v130, v131
	s_waitcnt lgkmcnt(0)
	v_add_f32_e32 v130, v130, v131
	v_fmamk_f32 v130, v130, 0x3b800000, v237
	v_cmp_gt_f32_e32 vcc, s11, v130
	v_mul_f32_e32 v131, 0x4f800000, v130
	s_nop 0
	v_cndmask_b32_e32 v130, v130, v131, vcc
	v_sqrt_f32_e32 v131, v130
	s_nop 0
	v_add_u32_e32 v132, -1, v131
	v_fma_f32 v133, -v132, v131, v130
	v_cmp_ge_f32_e64 s[4:5], 0, v133
	v_add_u32_e32 v133, 1, v131
	s_nop 0
	v_cndmask_b32_e64 v132, v131, v132, s[4:5]
	v_fma_f32 v131, -v133, v131, v130
	v_cmp_lt_f32_e64 s[4:5], 0, v131
	s_nop 1
	v_cndmask_b32_e64 v131, v132, v133, s[4:5]
	v_mul_f32_e32 v132, 0x37800000, v131
	v_cndmask_b32_e32 v131, v131, v132, vcc
	v_cmp_class_f32_e32 vcc, v130, v238
	s_nop 1
	v_cndmask_b32_e32 v130, v131, v130, vcc
	v_div_scale_f32 v131, s[4:5], v130, v130, 1.0
	v_rcp_f32_e32 v132, v131
	s_nop 0
	v_fma_f32 v133, -v131, v132, 1.0
	v_fmac_f32_e32 v132, v133, v132
	v_div_scale_f32 v133, vcc, 1.0, v130, 1.0
	v_mul_f32_e32 v134, v133, v132
	v_fma_f32 v135, -v131, v134, v133
	v_fmac_f32_e32 v134, v135, v132
	v_fma_f32 v131, -v131, v134, v133
	v_div_fmas_f32 v131, v131, v132, v134
	v_div_fixup_f32 v130, v131, v130, 1.0
	v_mul_f32_e32 v131, v99, v99
	v_fmac_f32_e32 v131, v115, v115
	v_fmac_f32_e32 v131, v83, v83
	v_fmac_f32_e32 v131, v67, v67
	v_fmac_f32_e32 v131, v51, v51
	v_fmac_f32_e32 v131, v35, v35
	v_mbcnt_lo_u32_b32 v132, -1, 0
	v_mbcnt_hi_u32_b32 v132, -1, v132
	v_fmac_f32_e32 v131, v19, v19
	v_lshlrev_b32_e32 v132, 2, v132
	v_fmac_f32_e32 v131, v3, v3
	v_xor_b32_e32 v132, 4, v132
	s_nop 1
	v_mov_b32_dpp v132, v131 quad_perm:[1,0,3,2] row_mask:0xf bank_mask:0xf
	s_waitcnt lgkmcnt(0)
	v_add_f32_e32 v131, v131, v132
	v_mbcnt_lo_u32_b32 v132, -1, 0
	v_mbcnt_hi_u32_b32 v132, -1, v132
	s_nop 0
	v_lshlrev_b32_e32 v132, 2, v132
	v_xor_b32_e32 v132, 8, v132
	s_nop 1
	v_mov_b32_dpp v132, v131 quad_perm:[2,3,0,1] row_mask:0xf bank_mask:0xf
	s_waitcnt lgkmcnt(0)
	v_add_f32_e32 v131, v131, v132
	v_mbcnt_lo_u32_b32 v132, -1, 0
	v_mbcnt_hi_u32_b32 v132, -1, v132
	s_nop 0
	v_lshlrev_b32_e32 v132, 2, v132
	v_xor_b32_e32 v132, 16, v132
	s_nop 1
	v_mov_b32_dpp v132, v131 row_half_mirror row_mask:0xf bank_mask:0xf
	s_waitcnt lgkmcnt(0)
	v_add_f32_e32 v131, v131, v132
	v_mbcnt_lo_u32_b32 v132, -1, 0
	v_mbcnt_hi_u32_b32 v132, -1, v132
	s_nop 0
	v_lshlrev_b32_e32 v132, 2, v132
	v_xor_b32_e32 v132, 32, v132
	s_nop 1
	v_mov_b32_dpp v132, v131 row_ror:8 row_mask:0xf bank_mask:0xf
	s_waitcnt lgkmcnt(0)
	v_add_f32_e32 v131, v131, v132
	v_mbcnt_lo_u32_b32 v132, -1, 0
	v_mbcnt_hi_u32_b32 v132, -1, v132
	s_nop 0
	v_lshlrev_b32_e32 v132, 2, v132
	v_xor_b32_e32 v132, 64, v132
	v_mov_b32_e32 v132, v131
	s_nop 1
	v_permlane16_swap_b32_e32 v131, v132
	s_waitcnt lgkmcnt(0)
	v_add_f32_e32 v131, v131, v132
	v_fmamk_f32 v131, v131, 0x3b800000, v237
	v_cmp_gt_f32_e32 vcc, s11, v131
	v_mul_f32_e32 v132, 0x4f800000, v131
	s_nop 0
	v_cndmask_b32_e32 v131, v131, v132, vcc
	v_sqrt_f32_e32 v132, v131
	s_nop 0
	v_add_u32_e32 v133, -1, v132
	v_fma_f32 v134, -v133, v132, v131
	v_cmp_ge_f32_e64 s[4:5], 0, v134
	v_add_u32_e32 v134, 1, v132
	s_nop 0
	v_cndmask_b32_e64 v133, v132, v133, s[4:5]
	v_fma_f32 v132, -v134, v132, v131
	v_cmp_lt_f32_e64 s[4:5], 0, v132
	s_nop 1
	v_cndmask_b32_e64 v132, v133, v134, s[4:5]
	v_mul_f32_e32 v133, 0x37800000, v132
	v_cndmask_b32_e32 v132, v132, v133, vcc
	v_cmp_class_f32_e32 vcc, v131, v238
	s_nop 1
	v_cndmask_b32_e32 v131, v132, v131, vcc
	v_div_scale_f32 v132, s[4:5], v131, v131, 1.0
	v_rcp_f32_e32 v133, v132
	s_nop 0
	v_fma_f32 v134, -v132, v133, 1.0
	v_fmac_f32_e32 v133, v134, v133
	v_div_scale_f32 v134, vcc, 1.0, v131, 1.0
	v_mul_f32_e32 v135, v134, v133
	v_fma_f32 v136, -v132, v135, v134
	v_fmac_f32_e32 v135, v136, v133
	v_fma_f32 v132, -v132, v135, v134
	v_div_fmas_f32 v132, v132, v133, v135
	v_div_fixup_f32 v131, v132, v131, 1.0
	v_mul_f32_e32 v132, v100, v100
	v_fmac_f32_e32 v132, v116, v116
	v_fmac_f32_e32 v132, v84, v84
	v_fmac_f32_e32 v132, v68, v68
	v_fmac_f32_e32 v132, v52, v52
	v_fmac_f32_e32 v132, v36, v36
	v_mbcnt_lo_u32_b32 v133, -1, 0
	v_mbcnt_hi_u32_b32 v133, -1, v133
	v_fmac_f32_e32 v132, v20, v20
	v_lshlrev_b32_e32 v133, 2, v133
	v_fmac_f32_e32 v132, v4, v4
	v_xor_b32_e32 v133, 4, v133
	s_nop 1
	v_mov_b32_dpp v133, v132 quad_perm:[1,0,3,2] row_mask:0xf bank_mask:0xf
	s_waitcnt lgkmcnt(0)
	v_add_f32_e32 v132, v132, v133
	v_mbcnt_lo_u32_b32 v133, -1, 0
	v_mbcnt_hi_u32_b32 v133, -1, v133
	s_nop 0
	v_lshlrev_b32_e32 v133, 2, v133
	v_xor_b32_e32 v133, 8, v133
	s_nop 1
	v_mov_b32_dpp v133, v132 quad_perm:[2,3,0,1] row_mask:0xf bank_mask:0xf
	s_waitcnt lgkmcnt(0)
; DI void ret_unit(LAS unsigned char* lds, bf16_t* MX, const bf16_t* VT, bf16_t* ST, int b, int hh, int qt, float lgf, float nlgb, int wave, const int mode) {
;     ...
;     for (int i = 0; i < 16; ++i) {
;         float ss = 0.f;
; #pragma unroll
;         for (int db = 0; db < 8; ++db) ss += z[db][i] * z[db][i];
;         ss += shx(ss, 1); ss += shx(ss, 2); ss += shx(ss, 4); ss += shx(ss, 8); ss += shx(ss, 16);
;         nrm[i] = 1.0f / sqrtf(ss * (1.0f / 256.0f) + EPS);
;     }
	v_add_f32_e32 v132, v132, v133
	v_mbcnt_lo_u32_b32 v133, -1, 0
	v_mbcnt_hi_u32_b32 v133, -1, v133
	s_nop 0
	v_lshlrev_b32_e32 v133, 2, v133
	v_xor_b32_e32 v133, 16, v133
	s_nop 1
	v_mov_b32_dpp v133, v132 row_half_mirror row_mask:0xf bank_mask:0xf
	s_waitcnt lgkmcnt(0)
	v_add_f32_e32 v132, v132, v133
	v_mbcnt_lo_u32_b32 v133, -1, 0
	v_mbcnt_hi_u32_b32 v133, -1, v133
	s_nop 0
	v_lshlrev_b32_e32 v133, 2, v133
	v_xor_b32_e32 v133, 32, v133
	s_nop 1
	v_mov_b32_dpp v133, v132 row_ror:8 row_mask:0xf bank_mask:0xf
	s_waitcnt lgkmcnt(0)
	v_add_f32_e32 v132, v132, v133
	v_mbcnt_lo_u32_b32 v133, -1, 0
	v_mbcnt_hi_u32_b32 v133, -1, v133
	s_nop 0
	v_lshlrev_b32_e32 v133, 2, v133
	v_xor_b32_e32 v133, 64, v133
	v_mov_b32_e32 v133, v132
	s_nop 1
	v_permlane16_swap_b32_e32 v132, v133
	s_waitcnt lgkmcnt(0)
	v_add_f32_e32 v132, v132, v133
	v_fmamk_f32 v132, v132, 0x3b800000, v237
	v_cmp_gt_f32_e32 vcc, s11, v132
	v_mul_f32_e32 v133, 0x4f800000, v132
	s_nop 0
	v_cndmask_b32_e32 v132, v132, v133, vcc
	v_sqrt_f32_e32 v133, v132
	s_nop 0
	v_add_u32_e32 v134, -1, v133
	v_fma_f32 v135, -v134, v133, v132
	v_cmp_ge_f32_e64 s[4:5], 0, v135
	v_add_u32_e32 v135, 1, v133
	s_nop 0
	v_cndmask_b32_e64 v134, v133, v134, s[4:5]
	v_fma_f32 v133, -v135, v133, v132
	v_cmp_lt_f32_e64 s[4:5], 0, v133
	s_nop 1
	v_cndmask_b32_e64 v133, v134, v135, s[4:5]
	v_mul_f32_e32 v134, 0x37800000, v133
	v_cndmask_b32_e32 v133, v133, v134, vcc
	v_cmp_class_f32_e32 vcc, v132, v238
	s_nop 1
	v_cndmask_b32_e32 v132, v133, v132, vcc
	v_div_scale_f32 v133, s[4:5], v132, v132, 1.0
	v_rcp_f32_e32 v134, v133
	s_nop 0
	v_fma_f32 v135, -v133, v134, 1.0
	v_fmac_f32_e32 v134, v135, v134
	v_div_scale_f32 v135, vcc, 1.0, v132, 1.0
	v_mul_f32_e32 v136, v135, v134
	v_fma_f32 v138, -v133, v136, v135
	v_fmac_f32_e32 v136, v138, v134
	v_fma_f32 v133, -v133, v136, v135
	v_div_fmas_f32 v133, v133, v134, v136
	v_div_fixup_f32 v132, v133, v132, 1.0
	v_mul_f32_e32 v133, v101, v101
	v_fmac_f32_e32 v133, v117, v117
	v_fmac_f32_e32 v133, v85, v85
	v_fmac_f32_e32 v133, v69, v69
	v_fmac_f32_e32 v133, v53, v53
	v_fmac_f32_e32 v133, v37, v37
	v_mbcnt_lo_u32_b32 v134, -1, 0
	v_mbcnt_hi_u32_b32 v134, -1, v134
	v_fmac_f32_e32 v133, v21, v21
	v_lshlrev_b32_e32 v134, 2, v134
	v_fmac_f32_e32 v133, v5, v5
	v_xor_b32_e32 v134, 4, v134
	s_nop 1
	v_mov_b32_dpp v134, v133 quad_perm:[1,0,3,2] row_mask:0xf bank_mask:0xf
	s_waitcnt lgkmcnt(0)
	v_add_f32_e32 v133, v133, v134
	v_mbcnt_lo_u32_b32 v134, -1, 0
	v_mbcnt_hi_u32_b32 v134, -1, v134
	s_nop 0
	v_lshlrev_b32_e32 v134, 2, v134
	v_xor_b32_e32 v134, 8, v134
	s_nop 1
	v_mov_b32_dpp v134, v133 quad_perm:[2,3,0,1] row_mask:0xf bank_mask:0xf
	s_waitcnt lgkmcnt(0)
	v_add_f32_e32 v133, v133, v134
	v_mbcnt_lo_u32_b32 v134, -1, 0
	v_mbcnt_hi_u32_b32 v134, -1, v134
	s_nop 0
	v_lshlrev_b32_e32 v134, 2, v134
	v_xor_b32_e32 v134, 16, v134
	s_nop 1
	v_mov_b32_dpp v134, v133 row_half_mirror row_mask:0xf bank_mask:0xf
	s_waitcnt lgkmcnt(0)
	v_add_f32_e32 v133, v133, v134
	v_mbcnt_lo_u32_b32 v134, -1, 0
	v_mbcnt_hi_u32_b32 v134, -1, v134
	s_nop 0
	v_lshlrev_b32_e32 v134, 2, v134
	v_xor_b32_e32 v134, 32, v134
	s_nop 1
	v_mov_b32_dpp v134, v133 row_ror:8 row_mask:0xf bank_mask:0xf
	s_waitcnt lgkmcnt(0)
	v_add_f32_e32 v133, v133, v134
	v_mbcnt_lo_u32_b32 v134, -1, 0
	v_mbcnt_hi_u32_b32 v134, -1, v134
	s_nop 0
	v_lshlrev_b32_e32 v134, 2, v134
	v_xor_b32_e32 v134, 64, v134
	v_mov_b32_e32 v134, v133
	s_nop 1
	v_permlane16_swap_b32_e32 v133, v134
	s_waitcnt lgkmcnt(0)
	v_add_f32_e32 v133, v133, v134
	v_fmamk_f32 v133, v133, 0x3b800000, v237
	v_cmp_gt_f32_e32 vcc, s11, v133
	v_mul_f32_e32 v134, 0x4f800000, v133
	s_nop 0
	v_cndmask_b32_e32 v133, v133, v134, vcc
	v_sqrt_f32_e32 v134, v133
	s_nop 0
	v_add_u32_e32 v135, -1, v134
	v_fma_f32 v136, -v135, v134, v133
	v_cmp_ge_f32_e64 s[4:5], 0, v136
	v_add_u32_e32 v136, 1, v134
	s_nop 0
	v_cndmask_b32_e64 v135, v134, v135, s[4:5]
	v_fma_f32 v134, -v136, v134, v133
	v_cmp_lt_f32_e64 s[4:5], 0, v134
	s_nop 1
	v_cndmask_b32_e64 v134, v135, v136, s[4:5]
	v_mul_f32_e32 v135, 0x37800000, v134
	v_cndmask_b32_e32 v134, v134, v135, vcc
	v_cmp_class_f32_e32 vcc, v133, v238
	s_nop 1
	v_cndmask_b32_e32 v133, v134, v133, vcc
	v_div_scale_f32 v134, s[4:5], v133, v133, 1.0
	v_rcp_f32_e32 v135, v134
	s_nop 0
	v_fma_f32 v136, -v134, v135, 1.0
	v_fmac_f32_e32 v135, v136, v135
	v_div_scale_f32 v136, vcc, 1.0, v133, 1.0
	v_mul_f32_e32 v138, v136, v135
	v_fma_f32 v139, -v134, v138, v136
	v_fmac_f32_e32 v138, v139, v135
	v_fma_f32 v134, -v134, v138, v136
	v_div_fmas_f32 v134, v134, v135, v138
	v_div_fixup_f32 v133, v134, v133, 1.0
	v_mul_f32_e32 v134, v102, v102
	v_fmac_f32_e32 v134, v118, v118
	v_fmac_f32_e32 v134, v86, v86
	v_fmac_f32_e32 v134, v70, v70
	v_fmac_f32_e32 v134, v54, v54
	v_fmac_f32_e32 v134, v38, v38
	v_mbcnt_lo_u32_b32 v135, -1, 0
	v_mbcnt_hi_u32_b32 v135, -1, v135
	v_fmac_f32_e32 v134, v22, v22
	v_lshlrev_b32_e32 v135, 2, v135
	v_fmac_f32_e32 v134, v6, v6
	v_xor_b32_e32 v135, 4, v135
	s_nop 1
	v_mov_b32_dpp v135, v134 quad_perm:[1,0,3,2] row_mask:0xf bank_mask:0xf
	s_waitcnt lgkmcnt(0)
	v_add_f32_e32 v134, v134, v135
	v_mbcnt_lo_u32_b32 v135, -1, 0
	v_mbcnt_hi_u32_b32 v135, -1, v135
	s_nop 0
	v_lshlrev_b32_e32 v135, 2, v135
	v_xor_b32_e32 v135, 8, v135
	s_nop 1
	v_mov_b32_dpp v135, v134 quad_perm:[2,3,0,1] row_mask:0xf bank_mask:0xf
	s_waitcnt lgkmcnt(0)
	v_add_f32_e32 v134, v134, v135
	v_mbcnt_lo_u32_b32 v135, -1, 0
	v_mbcnt_hi_u32_b32 v135, -1, v135
	s_nop 0
	v_lshlrev_b32_e32 v135, 2, v135
	v_xor_b32_e32 v135, 16, v135
	s_nop 1
	v_mov_b32_dpp v135, v134 row_half_mirror row_mask:0xf bank_mask:0xf
	s_waitcnt lgkmcnt(0)
; DI void ret_unit(LAS unsigned char* lds, bf16_t* MX, const bf16_t* VT, bf16_t* ST, int b, int hh, int qt, float lgf, float nlgb, int wave, const int mode) {
;     ...
;     for (int i = 0; i < 16; ++i) {
;         float ss = 0.f;
; #pragma unroll
;         for (int db = 0; db < 8; ++db) ss += z[db][i] * z[db][i];
;         ss += shx(ss, 1); ss += shx(ss, 2); ss += shx(ss, 4); ss += shx(ss, 8); ss += shx(ss, 16);
;         nrm[i] = 1.0f / sqrtf(ss * (1.0f / 256.0f) + EPS);
;     }
	v_add_f32_e32 v134, v134, v135
	v_mbcnt_lo_u32_b32 v135, -1, 0
	v_mbcnt_hi_u32_b32 v135, -1, v135
	s_nop 0
	v_lshlrev_b32_e32 v135, 2, v135
	v_xor_b32_e32 v135, 32, v135
	s_nop 1
	v_mov_b32_dpp v135, v134 row_ror:8 row_mask:0xf bank_mask:0xf
	s_waitcnt lgkmcnt(0)
	v_add_f32_e32 v134, v134, v135
	v_mbcnt_lo_u32_b32 v135, -1, 0
	v_mbcnt_hi_u32_b32 v135, -1, v135
	s_nop 0
	v_lshlrev_b32_e32 v135, 2, v135
	v_xor_b32_e32 v135, 64, v135
	v_mov_b32_e32 v135, v134
	s_nop 1
	v_permlane16_swap_b32_e32 v134, v135
	s_waitcnt lgkmcnt(0)
	v_add_f32_e32 v134, v134, v135
	v_fmamk_f32 v134, v134, 0x3b800000, v237
	v_cmp_gt_f32_e32 vcc, s11, v134
	v_mul_f32_e32 v135, 0x4f800000, v134
	s_nop 0
	v_cndmask_b32_e32 v134, v134, v135, vcc
	v_sqrt_f32_e32 v135, v134
	s_nop 0
	v_add_u32_e32 v136, -1, v135
	v_fma_f32 v138, -v136, v135, v134
	v_cmp_ge_f32_e64 s[4:5], 0, v138
	v_add_u32_e32 v138, 1, v135
	s_nop 0
	v_cndmask_b32_e64 v136, v135, v136, s[4:5]
	v_fma_f32 v135, -v138, v135, v134
	v_cmp_lt_f32_e64 s[4:5], 0, v135
	s_nop 1
	v_cndmask_b32_e64 v135, v136, v138, s[4:5]
	v_mul_f32_e32 v136, 0x37800000, v135
	v_cndmask_b32_e32 v135, v135, v136, vcc
	v_cmp_class_f32_e32 vcc, v134, v238
	s_nop 1
	v_cndmask_b32_e32 v134, v135, v134, vcc
	v_div_scale_f32 v135, s[4:5], v134, v134, 1.0
	v_rcp_f32_e32 v136, v135
	s_nop 0
	v_fma_f32 v138, -v135, v136, 1.0
	v_fmac_f32_e32 v136, v138, v136
	v_div_scale_f32 v138, vcc, 1.0, v134, 1.0
	v_mul_f32_e32 v139, v138, v136
	v_fma_f32 v140, -v135, v139, v138
	v_fmac_f32_e32 v139, v140, v136
	v_fma_f32 v135, -v135, v139, v138
	v_div_fmas_f32 v135, v135, v136, v139
	v_div_fixup_f32 v134, v135, v134, 1.0
	v_mul_f32_e32 v135, v103, v103
	v_fmac_f32_e32 v135, v119, v119
	v_fmac_f32_e32 v135, v87, v87
	v_fmac_f32_e32 v135, v71, v71
	v_fmac_f32_e32 v135, v55, v55
	v_fmac_f32_e32 v135, v39, v39
	v_mbcnt_lo_u32_b32 v136, -1, 0
	v_mbcnt_hi_u32_b32 v136, -1, v136
	v_fmac_f32_e32 v135, v23, v23
	v_lshlrev_b32_e32 v136, 2, v136
	v_fmac_f32_e32 v135, v7, v7
	v_xor_b32_e32 v136, 4, v136
	s_nop 1
	v_mov_b32_dpp v136, v135 quad_perm:[1,0,3,2] row_mask:0xf bank_mask:0xf
	s_waitcnt lgkmcnt(0)
	v_add_f32_e32 v135, v135, v136
	v_mbcnt_lo_u32_b32 v136, -1, 0
	v_mbcnt_hi_u32_b32 v136, -1, v136
	s_nop 0
	v_lshlrev_b32_e32 v136, 2, v136
	v_xor_b32_e32 v136, 8, v136
	s_nop 1
	v_mov_b32_dpp v136, v135 quad_perm:[2,3,0,1] row_mask:0xf bank_mask:0xf
	s_waitcnt lgkmcnt(0)
	v_add_f32_e32 v135, v135, v136
	v_mbcnt_lo_u32_b32 v136, -1, 0
	v_mbcnt_hi_u32_b32 v136, -1, v136
	s_nop 0
	v_lshlrev_b32_e32 v136, 2, v136
	v_xor_b32_e32 v136, 16, v136
	s_nop 1
	v_mov_b32_dpp v136, v135 row_half_mirror row_mask:0xf bank_mask:0xf
	s_waitcnt lgkmcnt(0)
	v_add_f32_e32 v135, v135, v136
	v_mbcnt_lo_u32_b32 v136, -1, 0
	v_mbcnt_hi_u32_b32 v136, -1, v136
	s_nop 0
	v_lshlrev_b32_e32 v136, 2, v136
	v_xor_b32_e32 v136, 32, v136
	s_nop 1
	v_mov_b32_dpp v136, v135 row_ror:8 row_mask:0xf bank_mask:0xf
	s_waitcnt lgkmcnt(0)
	v_add_f32_e32 v135, v135, v136
	v_mbcnt_lo_u32_b32 v136, -1, 0
	v_mbcnt_hi_u32_b32 v136, -1, v136
	s_nop 0
	v_lshlrev_b32_e32 v136, 2, v136
	v_xor_b32_e32 v136, 64, v136
	v_mov_b32_e32 v136, v135
	s_nop 1
	v_permlane16_swap_b32_e32 v135, v136
	s_waitcnt lgkmcnt(0)
	v_add_f32_e32 v135, v135, v136
	v_fmamk_f32 v135, v135, 0x3b800000, v237
	v_cmp_gt_f32_e32 vcc, s11, v135
	v_mul_f32_e32 v136, 0x4f800000, v135
	s_nop 0
	v_cndmask_b32_e32 v135, v135, v136, vcc
	v_sqrt_f32_e32 v136, v135
	s_nop 0
	v_add_u32_e32 v138, -1, v136
	v_fma_f32 v139, -v138, v136, v135
	v_cmp_ge_f32_e64 s[4:5], 0, v139
	v_add_u32_e32 v139, 1, v136
	s_nop 0
	v_cndmask_b32_e64 v138, v136, v138, s[4:5]
	v_fma_f32 v136, -v139, v136, v135
	v_cmp_lt_f32_e64 s[4:5], 0, v136
	s_nop 1
	v_cndmask_b32_e64 v136, v138, v139, s[4:5]
	v_mul_f32_e32 v138, 0x37800000, v136
	v_cndmask_b32_e32 v136, v136, v138, vcc
	v_cmp_class_f32_e32 vcc, v135, v238
	s_nop 1
	v_cndmask_b32_e32 v135, v136, v135, vcc
	v_div_scale_f32 v136, s[4:5], v135, v135, 1.0
	v_rcp_f32_e32 v138, v136
	s_nop 0
	v_fma_f32 v139, -v136, v138, 1.0
	v_fmac_f32_e32 v138, v139, v138
	v_div_scale_f32 v139, vcc, 1.0, v135, 1.0
	v_mul_f32_e32 v140, v139, v138
	v_fma_f32 v141, -v136, v140, v139
	v_fmac_f32_e32 v140, v141, v138
	v_fma_f32 v136, -v136, v140, v139
	v_div_fmas_f32 v136, v136, v138, v140
	v_div_fixup_f32 v135, v136, v135, 1.0
	v_mul_f32_e32 v136, v104, v104
	v_fmac_f32_e32 v136, v120, v120
	v_fmac_f32_e32 v136, v88, v88
	v_fmac_f32_e32 v136, v72, v72
	v_fmac_f32_e32 v136, v56, v56
	v_fmac_f32_e32 v136, v40, v40
	v_mbcnt_lo_u32_b32 v138, -1, 0
	v_mbcnt_hi_u32_b32 v138, -1, v138
	v_fmac_f32_e32 v136, v24, v24
	v_lshlrev_b32_e32 v138, 2, v138
	v_fmac_f32_e32 v136, v8, v8
	v_xor_b32_e32 v138, 4, v138
	s_nop 1
	v_mov_b32_dpp v138, v136 quad_perm:[1,0,3,2] row_mask:0xf bank_mask:0xf
	s_waitcnt lgkmcnt(0)
	v_add_f32_e32 v136, v136, v138
	v_mbcnt_lo_u32_b32 v138, -1, 0
	v_mbcnt_hi_u32_b32 v138, -1, v138
	s_nop 0
	v_lshlrev_b32_e32 v138, 2, v138
	v_xor_b32_e32 v138, 8, v138
	s_nop 1
	v_mov_b32_dpp v138, v136 quad_perm:[2,3,0,1] row_mask:0xf bank_mask:0xf
	s_waitcnt lgkmcnt(0)
	v_add_f32_e32 v136, v136, v138
	v_mbcnt_lo_u32_b32 v138, -1, 0
	v_mbcnt_hi_u32_b32 v138, -1, v138
	s_nop 0
	v_lshlrev_b32_e32 v138, 2, v138
	v_xor_b32_e32 v138, 16, v138
	s_nop 1
	v_mov_b32_dpp v138, v136 row_half_mirror row_mask:0xf bank_mask:0xf
	s_waitcnt lgkmcnt(0)
	v_add_f32_e32 v136, v136, v138
	v_mbcnt_lo_u32_b32 v138, -1, 0
	v_mbcnt_hi_u32_b32 v138, -1, v138
	s_nop 0
	v_lshlrev_b32_e32 v138, 2, v138
	v_xor_b32_e32 v138, 32, v138
	s_nop 1
	v_mov_b32_dpp v138, v136 row_ror:8 row_mask:0xf bank_mask:0xf
	s_waitcnt lgkmcnt(0)
; DI void ret_unit(LAS unsigned char* lds, bf16_t* MX, const bf16_t* VT, bf16_t* ST, int b, int hh, int qt, float lgf, float nlgb, int wave, const int mode) {
;     ...
;     for (int i = 0; i < 16; ++i) {
;         float ss = 0.f;
; #pragma unroll
;         for (int db = 0; db < 8; ++db) ss += z[db][i] * z[db][i];
;         ss += shx(ss, 1); ss += shx(ss, 2); ss += shx(ss, 4); ss += shx(ss, 8); ss += shx(ss, 16);
;         nrm[i] = 1.0f / sqrtf(ss * (1.0f / 256.0f) + EPS);
;     }
	v_add_f32_e32 v136, v136, v138
	v_mbcnt_lo_u32_b32 v138, -1, 0
	v_mbcnt_hi_u32_b32 v138, -1, v138
	s_nop 0
	v_lshlrev_b32_e32 v138, 2, v138
	v_xor_b32_e32 v138, 64, v138
	v_mov_b32_e32 v138, v136
	s_nop 1
	v_permlane16_swap_b32_e32 v136, v138
	s_waitcnt lgkmcnt(0)
	v_add_f32_e32 v136, v136, v138
	v_fmamk_f32 v136, v136, 0x3b800000, v237
	v_cmp_gt_f32_e32 vcc, s11, v136
	v_mul_f32_e32 v138, 0x4f800000, v136
	s_nop 0
	v_cndmask_b32_e32 v136, v136, v138, vcc
	v_sqrt_f32_e32 v138, v136
	s_nop 0
	v_add_u32_e32 v139, -1, v138
	v_fma_f32 v140, -v139, v138, v136
	v_cmp_ge_f32_e64 s[4:5], 0, v140
	v_add_u32_e32 v140, 1, v138
	s_nop 0
	v_cndmask_b32_e64 v139, v138, v139, s[4:5]
	v_fma_f32 v138, -v140, v138, v136
	v_cmp_lt_f32_e64 s[4:5], 0, v138
	s_nop 1
	v_cndmask_b32_e64 v138, v139, v140, s[4:5]
	v_mul_f32_e32 v139, 0x37800000, v138
	v_cndmask_b32_e32 v138, v138, v139, vcc
	v_cmp_class_f32_e32 vcc, v136, v238
	s_nop 1
	v_cndmask_b32_e32 v136, v138, v136, vcc
	v_div_scale_f32 v138, s[4:5], v136, v136, 1.0
	v_rcp_f32_e32 v139, v138
	s_nop 0
	v_fma_f32 v140, -v138, v139, 1.0
	v_fmac_f32_e32 v139, v140, v139
	v_div_scale_f32 v140, vcc, 1.0, v136, 1.0
	v_mul_f32_e32 v141, v140, v139
	v_fma_f32 v142, -v138, v141, v140
	v_fmac_f32_e32 v141, v142, v139
	v_fma_f32 v138, -v138, v141, v140
	v_div_fmas_f32 v138, v138, v139, v141
	v_div_fixup_f32 v136, v138, v136, 1.0
	v_mul_f32_e32 v138, v105, v105
	v_fmac_f32_e32 v138, v121, v121
	v_fmac_f32_e32 v138, v89, v89
	v_fmac_f32_e32 v138, v73, v73
	v_fmac_f32_e32 v138, v57, v57
	v_fmac_f32_e32 v138, v41, v41
	v_mbcnt_lo_u32_b32 v139, -1, 0
	v_mbcnt_hi_u32_b32 v139, -1, v139
	v_fmac_f32_e32 v138, v25, v25
	v_lshlrev_b32_e32 v139, 2, v139
	v_fmac_f32_e32 v138, v9, v9
	v_xor_b32_e32 v139, 4, v139
	s_nop 1
	v_mov_b32_dpp v139, v138 quad_perm:[1,0,3,2] row_mask:0xf bank_mask:0xf
	s_waitcnt lgkmcnt(0)
	v_add_f32_e32 v138, v138, v139
	v_mbcnt_lo_u32_b32 v139, -1, 0
	v_mbcnt_hi_u32_b32 v139, -1, v139
	s_nop 0
	v_lshlrev_b32_e32 v139, 2, v139
	v_xor_b32_e32 v139, 8, v139
	s_nop 1
	v_mov_b32_dpp v139, v138 quad_perm:[2,3,0,1] row_mask:0xf bank_mask:0xf
	s_waitcnt lgkmcnt(0)
	v_add_f32_e32 v138, v138, v139
	v_mbcnt_lo_u32_b32 v139, -1, 0
	v_mbcnt_hi_u32_b32 v139, -1, v139
	s_nop 0
	v_lshlrev_b32_e32 v139, 2, v139
	v_xor_b32_e32 v139, 16, v139
	s_nop 1
	v_mov_b32_dpp v139, v138 row_half_mirror row_mask:0xf bank_mask:0xf
	s_waitcnt lgkmcnt(0)
	v_add_f32_e32 v138, v138, v139
	v_mbcnt_lo_u32_b32 v139, -1, 0
	v_mbcnt_hi_u32_b32 v139, -1, v139
	s_nop 0
	v_lshlrev_b32_e32 v139, 2, v139
	v_xor_b32_e32 v139, 32, v139
	s_nop 1
	v_mov_b32_dpp v139, v138 row_ror:8 row_mask:0xf bank_mask:0xf
	s_waitcnt lgkmcnt(0)
	v_add_f32_e32 v138, v138, v139
	v_mbcnt_lo_u32_b32 v139, -1, 0
	v_mbcnt_hi_u32_b32 v139, -1, v139
	s_nop 0
	v_lshlrev_b32_e32 v139, 2, v139
	v_xor_b32_e32 v139, 64, v139
	v_mov_b32_e32 v139, v138
	s_nop 1
	v_permlane16_swap_b32_e32 v138, v139
	s_waitcnt lgkmcnt(0)
	v_add_f32_e32 v138, v138, v139
	v_fmamk_f32 v138, v138, 0x3b800000, v237
	v_cmp_gt_f32_e32 vcc, s11, v138
	v_mul_f32_e32 v139, 0x4f800000, v138
	s_nop 0
	v_cndmask_b32_e32 v138, v138, v139, vcc
	v_sqrt_f32_e32 v139, v138
	s_nop 0
	v_add_u32_e32 v140, -1, v139
	v_fma_f32 v141, -v140, v139, v138
	v_cmp_ge_f32_e64 s[4:5], 0, v141
	v_add_u32_e32 v141, 1, v139
	s_nop 0
	v_cndmask_b32_e64 v140, v139, v140, s[4:5]
	v_fma_f32 v139, -v141, v139, v138
	v_cmp_lt_f32_e64 s[4:5], 0, v139
	s_nop 1
	v_cndmask_b32_e64 v139, v140, v141, s[4:5]
	v_mul_f32_e32 v140, 0x37800000, v139
	v_cndmask_b32_e32 v139, v139, v140, vcc
	v_cmp_class_f32_e32 vcc, v138, v238
	s_nop 1
	v_cndmask_b32_e32 v138, v139, v138, vcc
	v_div_scale_f32 v139, s[4:5], v138, v138, 1.0
	v_rcp_f32_e32 v140, v139
	s_nop 0
	v_fma_f32 v141, -v139, v140, 1.0
	v_fmac_f32_e32 v140, v141, v140
	v_div_scale_f32 v141, vcc, 1.0, v138, 1.0
	v_mul_f32_e32 v142, v141, v140
	v_fma_f32 v143, -v139, v142, v141
	v_fmac_f32_e32 v142, v143, v140
	v_fma_f32 v139, -v139, v142, v141
	v_div_fmas_f32 v139, v139, v140, v142
	v_div_fixup_f32 v138, v139, v138, 1.0
	v_mul_f32_e32 v139, v106, v106
	v_fmac_f32_e32 v139, v122, v122
	v_fmac_f32_e32 v139, v90, v90
	v_fmac_f32_e32 v139, v74, v74
	v_fmac_f32_e32 v139, v58, v58
	v_fmac_f32_e32 v139, v42, v42
	v_mbcnt_lo_u32_b32 v140, -1, 0
	v_mbcnt_hi_u32_b32 v140, -1, v140
	v_fmac_f32_e32 v139, v26, v26
	v_lshlrev_b32_e32 v140, 2, v140
	v_fmac_f32_e32 v139, v10, v10
	v_xor_b32_e32 v140, 4, v140
	s_nop 1
	v_mov_b32_dpp v140, v139 quad_perm:[1,0,3,2] row_mask:0xf bank_mask:0xf
	s_waitcnt lgkmcnt(0)
	v_add_f32_e32 v139, v139, v140
	v_mbcnt_lo_u32_b32 v140, -1, 0
	v_mbcnt_hi_u32_b32 v140, -1, v140
	s_nop 0
	v_lshlrev_b32_e32 v140, 2, v140
	v_xor_b32_e32 v140, 8, v140
	s_nop 1
	v_mov_b32_dpp v140, v139 quad_perm:[2,3,0,1] row_mask:0xf bank_mask:0xf
	s_waitcnt lgkmcnt(0)
	v_add_f32_e32 v139, v139, v140
	v_mbcnt_lo_u32_b32 v140, -1, 0
	v_mbcnt_hi_u32_b32 v140, -1, v140
	s_nop 0
	v_lshlrev_b32_e32 v140, 2, v140
	v_xor_b32_e32 v140, 16, v140
	s_nop 1
	v_mov_b32_dpp v140, v139 row_half_mirror row_mask:0xf bank_mask:0xf
	s_waitcnt lgkmcnt(0)
	v_add_f32_e32 v139, v139, v140
	v_mbcnt_lo_u32_b32 v140, -1, 0
	v_mbcnt_hi_u32_b32 v140, -1, v140
	s_nop 0
	v_lshlrev_b32_e32 v140, 2, v140
	v_xor_b32_e32 v140, 32, v140
	s_nop 1
	v_mov_b32_dpp v140, v139 row_ror:8 row_mask:0xf bank_mask:0xf
	s_waitcnt lgkmcnt(0)
	v_add_f32_e32 v139, v139, v140
	v_mbcnt_lo_u32_b32 v140, -1, 0
	v_mbcnt_hi_u32_b32 v140, -1, v140
	s_nop 0
	v_lshlrev_b32_e32 v140, 2, v140
	v_xor_b32_e32 v140, 64, v140
	v_mov_b32_e32 v140, v139
	s_nop 1
	v_permlane16_swap_b32_e32 v139, v140
	s_waitcnt lgkmcnt(0)
; DI void ret_unit(LAS unsigned char* lds, bf16_t* MX, const bf16_t* VT, bf16_t* ST, int b, int hh, int qt, float lgf, float nlgb, int wave, const int mode) {
;     ...
;     for (int i = 0; i < 16; ++i) {
;         float ss = 0.f;
; #pragma unroll
;         for (int db = 0; db < 8; ++db) ss += z[db][i] * z[db][i];
;         ss += shx(ss, 1); ss += shx(ss, 2); ss += shx(ss, 4); ss += shx(ss, 8); ss += shx(ss, 16);
;         nrm[i] = 1.0f / sqrtf(ss * (1.0f / 256.0f) + EPS);
;     }
	v_add_f32_e32 v139, v139, v140
	v_fmamk_f32 v139, v139, 0x3b800000, v237
	v_cmp_gt_f32_e32 vcc, s11, v139
	v_mul_f32_e32 v140, 0x4f800000, v139
	s_nop 0
	v_cndmask_b32_e32 v139, v139, v140, vcc
	v_sqrt_f32_e32 v140, v139
	s_nop 0
	v_add_u32_e32 v141, -1, v140
	v_fma_f32 v142, -v141, v140, v139
	v_cmp_ge_f32_e64 s[4:5], 0, v142
	v_add_u32_e32 v142, 1, v140
	s_nop 0
	v_cndmask_b32_e64 v141, v140, v141, s[4:5]
	v_fma_f32 v140, -v142, v140, v139
	v_cmp_lt_f32_e64 s[4:5], 0, v140
	s_nop 1
	v_cndmask_b32_e64 v140, v141, v142, s[4:5]
	v_mul_f32_e32 v141, 0x37800000, v140
	v_cndmask_b32_e32 v140, v140, v141, vcc
	v_cmp_class_f32_e32 vcc, v139, v238
	s_nop 1
	v_cndmask_b32_e32 v139, v140, v139, vcc
	v_div_scale_f32 v140, s[4:5], v139, v139, 1.0
	v_rcp_f32_e32 v141, v140
	s_nop 0
	v_fma_f32 v142, -v140, v141, 1.0
	v_fmac_f32_e32 v141, v142, v141
	v_div_scale_f32 v142, vcc, 1.0, v139, 1.0
	v_mul_f32_e32 v143, v142, v141
	v_fma_f32 v144, -v140, v143, v142
	v_fmac_f32_e32 v143, v144, v141
	v_fma_f32 v140, -v140, v143, v142
	v_div_fmas_f32 v140, v140, v141, v143
	v_div_fixup_f32 v139, v140, v139, 1.0
	v_mul_f32_e32 v140, v107, v107
	v_fmac_f32_e32 v140, v123, v123
	v_fmac_f32_e32 v140, v91, v91
	v_fmac_f32_e32 v140, v75, v75
	v_fmac_f32_e32 v140, v59, v59
	v_fmac_f32_e32 v140, v43, v43
	v_mbcnt_lo_u32_b32 v141, -1, 0
	v_mbcnt_hi_u32_b32 v141, -1, v141
	v_fmac_f32_e32 v140, v27, v27
	v_lshlrev_b32_e32 v141, 2, v141
	v_fmac_f32_e32 v140, v11, v11
	v_xor_b32_e32 v141, 4, v141
	s_nop 1
	v_mov_b32_dpp v141, v140 quad_perm:[1,0,3,2] row_mask:0xf bank_mask:0xf
	s_waitcnt lgkmcnt(0)
	v_add_f32_e32 v140, v140, v141
	v_mbcnt_lo_u32_b32 v141, -1, 0
	v_mbcnt_hi_u32_b32 v141, -1, v141
	s_nop 0
	v_lshlrev_b32_e32 v141, 2, v141
	v_xor_b32_e32 v141, 8, v141
	s_nop 1
	v_mov_b32_dpp v141, v140 quad_perm:[2,3,0,1] row_mask:0xf bank_mask:0xf
	s_waitcnt lgkmcnt(0)
	v_add_f32_e32 v140, v140, v141
	v_mbcnt_lo_u32_b32 v141, -1, 0
	v_mbcnt_hi_u32_b32 v141, -1, v141
	s_nop 0
	v_lshlrev_b32_e32 v141, 2, v141
	v_xor_b32_e32 v141, 16, v141
	s_nop 1
	v_mov_b32_dpp v141, v140 row_half_mirror row_mask:0xf bank_mask:0xf
	s_waitcnt lgkmcnt(0)
	v_add_f32_e32 v140, v140, v141
	v_mbcnt_lo_u32_b32 v141, -1, 0
	v_mbcnt_hi_u32_b32 v141, -1, v141
	s_nop 0
	v_lshlrev_b32_e32 v141, 2, v141
	v_xor_b32_e32 v141, 32, v141
	s_nop 1
	v_mov_b32_dpp v141, v140 row_ror:8 row_mask:0xf bank_mask:0xf
	s_waitcnt lgkmcnt(0)
	v_add_f32_e32 v140, v140, v141
	v_mbcnt_lo_u32_b32 v141, -1, 0
	v_mbcnt_hi_u32_b32 v141, -1, v141
	s_nop 0
	v_lshlrev_b32_e32 v141, 2, v141
	v_xor_b32_e32 v141, 64, v141
	v_mov_b32_e32 v141, v140
	s_nop 1
	v_permlane16_swap_b32_e32 v140, v141
	s_waitcnt lgkmcnt(0)
	v_add_f32_e32 v140, v140, v141
	v_fmamk_f32 v140, v140, 0x3b800000, v237
	v_cmp_gt_f32_e32 vcc, s11, v140
	v_mul_f32_e32 v141, 0x4f800000, v140
	s_nop 0
	v_cndmask_b32_e32 v140, v140, v141, vcc
	v_sqrt_f32_e32 v141, v140
	s_nop 0
	v_add_u32_e32 v142, -1, v141
	v_fma_f32 v143, -v142, v141, v140
	v_cmp_ge_f32_e64 s[4:5], 0, v143
	v_add_u32_e32 v143, 1, v141
	s_nop 0
	v_cndmask_b32_e64 v142, v141, v142, s[4:5]
	v_fma_f32 v141, -v143, v141, v140
	v_cmp_lt_f32_e64 s[4:5], 0, v141
	s_nop 1
	v_cndmask_b32_e64 v141, v142, v143, s[4:5]
	v_mul_f32_e32 v142, 0x37800000, v141
	v_cndmask_b32_e32 v141, v141, v142, vcc
	v_cmp_class_f32_e32 vcc, v140, v238
	s_nop 1
	v_cndmask_b32_e32 v140, v141, v140, vcc
	v_div_scale_f32 v141, s[4:5], v140, v140, 1.0
	v_rcp_f32_e32 v142, v141
	s_nop 0
	v_fma_f32 v143, -v141, v142, 1.0
	v_fmac_f32_e32 v142, v143, v142
	v_div_scale_f32 v143, vcc, 1.0, v140, 1.0
	v_mul_f32_e32 v144, v143, v142
	v_fma_f32 v145, -v141, v144, v143
	v_fmac_f32_e32 v144, v145, v142
	v_fma_f32 v141, -v141, v144, v143
	v_div_fmas_f32 v141, v141, v142, v144
	v_div_fixup_f32 v140, v141, v140, 1.0
	v_mul_f32_e32 v141, v108, v108
	v_fmac_f32_e32 v141, v124, v124
	v_fmac_f32_e32 v141, v92, v92
	v_fmac_f32_e32 v141, v76, v76
	v_fmac_f32_e32 v141, v60, v60
	v_fmac_f32_e32 v141, v44, v44
	v_mbcnt_lo_u32_b32 v142, -1, 0
	v_mbcnt_hi_u32_b32 v142, -1, v142
	v_fmac_f32_e32 v141, v28, v28
	v_lshlrev_b32_e32 v142, 2, v142
	v_fmac_f32_e32 v141, v12, v12
	v_xor_b32_e32 v142, 4, v142
	s_nop 1
	v_mov_b32_dpp v142, v141 quad_perm:[1,0,3,2] row_mask:0xf bank_mask:0xf
	s_waitcnt lgkmcnt(0)
	v_add_f32_e32 v141, v141, v142
	v_mbcnt_lo_u32_b32 v142, -1, 0
	v_mbcnt_hi_u32_b32 v142, -1, v142
	s_nop 0
	v_lshlrev_b32_e32 v142, 2, v142
	v_xor_b32_e32 v142, 8, v142
	s_nop 1
	v_mov_b32_dpp v142, v141 quad_perm:[2,3,0,1] row_mask:0xf bank_mask:0xf
	s_waitcnt lgkmcnt(0)
	v_add_f32_e32 v141, v141, v142
	v_mbcnt_lo_u32_b32 v142, -1, 0
	v_mbcnt_hi_u32_b32 v142, -1, v142
	s_nop 0
	v_lshlrev_b32_e32 v142, 2, v142
	v_xor_b32_e32 v142, 16, v142
	s_nop 1
	v_mov_b32_dpp v142, v141 row_half_mirror row_mask:0xf bank_mask:0xf
	s_waitcnt lgkmcnt(0)
	v_add_f32_e32 v141, v141, v142
	v_mbcnt_lo_u32_b32 v142, -1, 0
	v_mbcnt_hi_u32_b32 v142, -1, v142
	s_nop 0
	v_lshlrev_b32_e32 v142, 2, v142
	v_xor_b32_e32 v142, 32, v142
	s_nop 1
	v_mov_b32_dpp v142, v141 row_ror:8 row_mask:0xf bank_mask:0xf
	s_waitcnt lgkmcnt(0)
	v_add_f32_e32 v141, v141, v142
	v_mbcnt_lo_u32_b32 v142, -1, 0
	v_mbcnt_hi_u32_b32 v142, -1, v142
	s_nop 0
	v_lshlrev_b32_e32 v142, 2, v142
	v_xor_b32_e32 v142, 64, v142
	v_mov_b32_e32 v142, v141
	s_nop 1
	v_permlane16_swap_b32_e32 v141, v142
	s_waitcnt lgkmcnt(0)
; DI void ret_unit(LAS unsigned char* lds, bf16_t* MX, const bf16_t* VT, bf16_t* ST, int b, int hh, int qt, float lgf, float nlgb, int wave, const int mode) {
;     ...
;     for (int i = 0; i < 16; ++i) {
;         float ss = 0.f;
; #pragma unroll
;         for (int db = 0; db < 8; ++db) ss += z[db][i] * z[db][i];
;         ss += shx(ss, 1); ss += shx(ss, 2); ss += shx(ss, 4); ss += shx(ss, 8); ss += shx(ss, 16);
;         nrm[i] = 1.0f / sqrtf(ss * (1.0f / 256.0f) + EPS);
;     }
	v_add_f32_e32 v141, v141, v142
	v_fmamk_f32 v141, v141, 0x3b800000, v237
	v_cmp_gt_f32_e32 vcc, s11, v141
	v_mul_f32_e32 v142, 0x4f800000, v141
	s_nop 0
	v_cndmask_b32_e32 v141, v141, v142, vcc
	v_sqrt_f32_e32 v142, v141
	s_nop 0
	v_add_u32_e32 v143, -1, v142
	v_fma_f32 v144, -v143, v142, v141
	v_cmp_ge_f32_e64 s[4:5], 0, v144
	v_add_u32_e32 v144, 1, v142
	s_nop 0
	v_cndmask_b32_e64 v143, v142, v143, s[4:5]
	v_fma_f32 v142, -v144, v142, v141
	v_cmp_lt_f32_e64 s[4:5], 0, v142
	s_nop 1
	v_cndmask_b32_e64 v142, v143, v144, s[4:5]
	v_mul_f32_e32 v143, 0x37800000, v142
	v_cndmask_b32_e32 v142, v142, v143, vcc
	v_cmp_class_f32_e32 vcc, v141, v238
	s_nop 1
	v_cndmask_b32_e32 v141, v142, v141, vcc
	v_div_scale_f32 v142, s[4:5], v141, v141, 1.0
	v_rcp_f32_e32 v143, v142
	s_nop 0
	v_fma_f32 v144, -v142, v143, 1.0
	v_fmac_f32_e32 v143, v144, v143
	v_div_scale_f32 v144, vcc, 1.0, v141, 1.0
	v_mul_f32_e32 v145, v144, v143
	v_fma_f32 v146, -v142, v145, v144
	v_fmac_f32_e32 v145, v146, v143
	v_fma_f32 v142, -v142, v145, v144
	v_div_fmas_f32 v142, v142, v143, v145
	v_div_fixup_f32 v141, v142, v141, 1.0
	v_mul_f32_e32 v142, v109, v109
	v_fmac_f32_e32 v142, v125, v125
	v_fmac_f32_e32 v142, v93, v93
	v_fmac_f32_e32 v142, v77, v77
	v_fmac_f32_e32 v142, v61, v61
	v_fmac_f32_e32 v142, v45, v45
	v_mbcnt_lo_u32_b32 v143, -1, 0
	v_mbcnt_hi_u32_b32 v143, -1, v143
	v_fmac_f32_e32 v142, v29, v29
	v_lshlrev_b32_e32 v143, 2, v143
	v_fmac_f32_e32 v142, v13, v13
	v_xor_b32_e32 v143, 4, v143
	s_nop 1
	v_mov_b32_dpp v143, v142 quad_perm:[1,0,3,2] row_mask:0xf bank_mask:0xf
	s_waitcnt lgkmcnt(0)
	v_add_f32_e32 v142, v142, v143
	v_mbcnt_lo_u32_b32 v143, -1, 0
	v_mbcnt_hi_u32_b32 v143, -1, v143
	s_nop 0
	v_lshlrev_b32_e32 v143, 2, v143
	v_xor_b32_e32 v143, 8, v143
	s_nop 1
	v_mov_b32_dpp v143, v142 quad_perm:[2,3,0,1] row_mask:0xf bank_mask:0xf
	s_waitcnt lgkmcnt(0)
	v_add_f32_e32 v142, v142, v143
	v_mbcnt_lo_u32_b32 v143, -1, 0
	v_mbcnt_hi_u32_b32 v143, -1, v143
	s_nop 0
	v_lshlrev_b32_e32 v143, 2, v143
	v_xor_b32_e32 v143, 16, v143
	s_nop 1
	v_mov_b32_dpp v143, v142 row_half_mirror row_mask:0xf bank_mask:0xf
	s_waitcnt lgkmcnt(0)
	v_add_f32_e32 v142, v142, v143
	v_mbcnt_lo_u32_b32 v143, -1, 0
	v_mbcnt_hi_u32_b32 v143, -1, v143
	s_nop 0
	v_lshlrev_b32_e32 v143, 2, v143
	v_xor_b32_e32 v143, 32, v143
	s_nop 1
	v_mov_b32_dpp v143, v142 row_ror:8 row_mask:0xf bank_mask:0xf
	s_waitcnt lgkmcnt(0)
	v_add_f32_e32 v142, v142, v143
	v_mbcnt_lo_u32_b32 v143, -1, 0
	v_mbcnt_hi_u32_b32 v143, -1, v143
	s_nop 0
	v_lshlrev_b32_e32 v143, 2, v143
	v_xor_b32_e32 v143, 64, v143
	v_mov_b32_e32 v143, v142
	s_nop 1
	v_permlane16_swap_b32_e32 v142, v143
	s_waitcnt lgkmcnt(0)
	v_add_f32_e32 v142, v142, v143
	v_fmamk_f32 v142, v142, 0x3b800000, v237
	v_cmp_gt_f32_e32 vcc, s11, v142
	v_mul_f32_e32 v143, 0x4f800000, v142
	s_nop 0
	v_cndmask_b32_e32 v142, v142, v143, vcc
	v_sqrt_f32_e32 v143, v142
	s_nop 0
	v_add_u32_e32 v144, -1, v143
	v_fma_f32 v145, -v144, v143, v142
	v_cmp_ge_f32_e64 s[4:5], 0, v145
	v_add_u32_e32 v145, 1, v143
	s_nop 0
	v_cndmask_b32_e64 v144, v143, v144, s[4:5]
	v_fma_f32 v143, -v145, v143, v142
	v_cmp_lt_f32_e64 s[4:5], 0, v143
	s_nop 1
	v_cndmask_b32_e64 v143, v144, v145, s[4:5]
	v_mul_f32_e32 v144, 0x37800000, v143
	v_cndmask_b32_e32 v143, v143, v144, vcc
	v_cmp_class_f32_e32 vcc, v142, v238
	s_nop 1
	v_cndmask_b32_e32 v142, v143, v142, vcc
	v_div_scale_f32 v143, s[4:5], v142, v142, 1.0
	v_rcp_f32_e32 v144, v143
	s_nop 0
	v_fma_f32 v145, -v143, v144, 1.0
	v_fmac_f32_e32 v144, v145, v144
	v_div_scale_f32 v145, vcc, 1.0, v142, 1.0
	v_mul_f32_e32 v146, v145, v144
	v_fma_f32 v147, -v143, v146, v145
	v_fmac_f32_e32 v146, v147, v144
	v_fma_f32 v143, -v143, v146, v145
	v_div_fmas_f32 v143, v143, v144, v146
	v_div_fixup_f32 v142, v143, v142, 1.0
	v_mul_f32_e32 v143, v110, v110
	v_fmac_f32_e32 v143, v126, v126
	v_fmac_f32_e32 v143, v94, v94
	v_fmac_f32_e32 v143, v78, v78
	v_fmac_f32_e32 v143, v62, v62
	v_fmac_f32_e32 v143, v46, v46
	v_mbcnt_lo_u32_b32 v144, -1, 0
	v_mbcnt_hi_u32_b32 v144, -1, v144
	v_fmac_f32_e32 v143, v30, v30
	v_lshlrev_b32_e32 v144, 2, v144
	v_fmac_f32_e32 v143, v14, v14
	v_xor_b32_e32 v144, 4, v144
	s_nop 1
	v_mov_b32_dpp v144, v143 quad_perm:[1,0,3,2] row_mask:0xf bank_mask:0xf
	s_waitcnt lgkmcnt(0)
	v_add_f32_e32 v143, v143, v144
	v_mbcnt_lo_u32_b32 v144, -1, 0
	v_mbcnt_hi_u32_b32 v144, -1, v144
	s_nop 0
	v_lshlrev_b32_e32 v144, 2, v144
	v_xor_b32_e32 v144, 8, v144
	s_nop 1
	v_mov_b32_dpp v144, v143 quad_perm:[2,3,0,1] row_mask:0xf bank_mask:0xf
	s_waitcnt lgkmcnt(0)
	v_add_f32_e32 v143, v143, v144
	v_mbcnt_lo_u32_b32 v144, -1, 0
	v_mbcnt_hi_u32_b32 v144, -1, v144
	s_nop 0
	v_lshlrev_b32_e32 v144, 2, v144
	v_xor_b32_e32 v144, 16, v144
	s_nop 1
	v_mov_b32_dpp v144, v143 row_half_mirror row_mask:0xf bank_mask:0xf
	s_waitcnt lgkmcnt(0)
	v_add_f32_e32 v143, v143, v144
	v_mbcnt_lo_u32_b32 v144, -1, 0
	v_mbcnt_hi_u32_b32 v144, -1, v144
	s_nop 0
	v_lshlrev_b32_e32 v144, 2, v144
	v_xor_b32_e32 v144, 32, v144
	s_nop 1
	v_mov_b32_dpp v144, v143 row_ror:8 row_mask:0xf bank_mask:0xf
	s_waitcnt lgkmcnt(0)
	v_add_f32_e32 v143, v143, v144
	v_mbcnt_lo_u32_b32 v144, -1, 0
	v_mbcnt_hi_u32_b32 v144, -1, v144
	s_nop 0
	v_lshlrev_b32_e32 v144, 2, v144
	v_xor_b32_e32 v144, 64, v144
	v_mov_b32_e32 v144, v143
	s_nop 1
	v_permlane16_swap_b32_e32 v143, v144
	s_waitcnt lgkmcnt(0)
; #define LAS __attribute__((address_space(3)))
; DI unsigned f2bf(float f) { unsigned u = __builtin_bit_cast(unsigned, f); return (u + 0x7fffu + ((u >> 16) & 1u)) >> 16; }
; DI void ret_unit(LAS unsigned char* lds, bf16_t* MX, const bf16_t* VT, bf16_t* ST, int b, int hh, int qt, float lgf, float nlgb, int wave, const int mode) {
;     ...
;     for (int i = 0; i < 16; ++i) {
;         float ss = 0.f;
; #pragma unroll
;         for (int db = 0; db < 8; ++db) ss += z[db][i] * z[db][i];
;         ss += shx(ss, 1); ss += shx(ss, 2); ss += shx(ss, 4); ss += shx(ss, 8); ss += shx(ss, 16);
;         nrm[i] = 1.0f / sqrtf(ss * (1.0f / 256.0f) + EPS);
;     }
;     __syncthreads();
;     LAS unsigned char* T = lds + wave * 8704;
; #pragma unroll
;     for (int hf = 0; hf < 2; ++hf) {
; #pragma unroll
;         for (int i = 0; i < 16; ++i) { const int q = (i & 3) + 8 * (i >> 2) + 4 * he;
; #pragma unroll
;             for (int d4 = 0; d4 < 4; ++d4) *(LAS bf16_t*)(T + q * 272 + (d4 * 32 + re) * 2) = (bf16_t)f2bf(z[hf * 4 + d4][i] * nrm[i]); }
	v_add_f32_e32 v143, v143, v144
	v_fmamk_f32 v143, v143, 0x3b800000, v237
	v_cmp_gt_f32_e32 vcc, s11, v143
	v_mul_f32_e32 v144, 0x4f800000, v143
	s_nop 0
	v_cndmask_b32_e32 v143, v143, v144, vcc
	v_sqrt_f32_e32 v144, v143
	s_nop 0
	v_add_u32_e32 v145, -1, v144
	v_fma_f32 v146, -v145, v144, v143
	v_cmp_ge_f32_e64 s[4:5], 0, v146
	v_add_u32_e32 v146, 1, v144
	s_nop 0
	v_cndmask_b32_e64 v145, v144, v145, s[4:5]
	v_fma_f32 v144, -v146, v144, v143
	v_cmp_lt_f32_e64 s[4:5], 0, v144
	s_nop 1
	v_cndmask_b32_e64 v144, v145, v146, s[4:5]
	v_mul_f32_e32 v145, 0x37800000, v144
	v_cndmask_b32_e32 v144, v144, v145, vcc
	v_cmp_class_f32_e32 vcc, v143, v238
	s_nop 1
	v_cndmask_b32_e32 v143, v144, v143, vcc
	v_div_scale_f32 v144, s[4:5], v143, v143, 1.0
	v_rcp_f32_e32 v145, v144
	s_nop 0
	v_fma_f32 v146, -v144, v145, 1.0
	v_fmac_f32_e32 v145, v146, v145
	v_div_scale_f32 v146, vcc, 1.0, v143, 1.0
	v_mul_f32_e32 v147, v146, v145
	v_fma_f32 v148, -v144, v147, v146
	v_fmac_f32_e32 v147, v148, v145
	v_fma_f32 v144, -v144, v147, v146
	v_div_fmas_f32 v144, v144, v145, v147
	v_div_fixup_f32 v143, v144, v143, 1.0
	v_mul_f32_e32 v144, v111, v111
	v_fmac_f32_e32 v144, v127, v127
	v_fmac_f32_e32 v144, v95, v95
	v_fmac_f32_e32 v144, v79, v79
	v_fmac_f32_e32 v144, v63, v63
	v_fmac_f32_e32 v144, v47, v47
	v_mbcnt_lo_u32_b32 v145, -1, 0
	v_mbcnt_hi_u32_b32 v145, -1, v145
	v_fmac_f32_e32 v144, v31, v31
	v_lshlrev_b32_e32 v145, 2, v145
	v_fmac_f32_e32 v144, v15, v15
	v_xor_b32_e32 v145, 4, v145
	s_nop 1
	v_mov_b32_dpp v145, v144 quad_perm:[1,0,3,2] row_mask:0xf bank_mask:0xf
	s_waitcnt lgkmcnt(0)
	v_add_f32_e32 v144, v144, v145
	v_mbcnt_lo_u32_b32 v145, -1, 0
	v_mbcnt_hi_u32_b32 v145, -1, v145
	s_nop 0
	v_lshlrev_b32_e32 v145, 2, v145
	v_xor_b32_e32 v145, 8, v145
	s_nop 1
	v_mov_b32_dpp v145, v144 quad_perm:[2,3,0,1] row_mask:0xf bank_mask:0xf
	s_waitcnt lgkmcnt(0)
	v_add_f32_e32 v144, v144, v145
	v_mbcnt_lo_u32_b32 v145, -1, 0
	v_mbcnt_hi_u32_b32 v145, -1, v145
	s_nop 0
	v_lshlrev_b32_e32 v145, 2, v145
	v_xor_b32_e32 v145, 16, v145
	s_nop 1
	v_mov_b32_dpp v145, v144 row_half_mirror row_mask:0xf bank_mask:0xf
	s_waitcnt lgkmcnt(0)
	v_add_f32_e32 v144, v144, v145
	v_mbcnt_lo_u32_b32 v145, -1, 0
	v_mbcnt_hi_u32_b32 v145, -1, v145
	s_nop 0
	v_lshlrev_b32_e32 v145, 2, v145
	v_xor_b32_e32 v145, 32, v145
	s_nop 1
	v_mov_b32_dpp v145, v144 row_ror:8 row_mask:0xf bank_mask:0xf
	s_waitcnt lgkmcnt(0)
	v_add_f32_e32 v144, v144, v145
	v_mbcnt_lo_u32_b32 v145, -1, 0
	v_mbcnt_hi_u32_b32 v145, -1, v145
	s_waitcnt vmcnt(0)
	v_lshlrev_b32_e32 v145, 2, v145
	v_xor_b32_e32 v145, 64, v145
	v_mov_b32_e32 v145, v144
	s_nop 1
	v_permlane16_swap_b32_e32 v144, v145
	s_barrier
	s_waitcnt lgkmcnt(0)
	v_add_f32_e32 v144, v144, v145
	v_fmamk_f32 v144, v144, 0x3b800000, v237
	v_cmp_gt_f32_e32 vcc, s11, v144
	v_mul_f32_e32 v145, 0x4f800000, v144
	s_movk_i32 s11, 0x110
	v_cndmask_b32_e32 v144, v144, v145, vcc
	v_sqrt_f32_e32 v145, v144
	s_nop 0
	v_add_u32_e32 v146, -1, v145
	v_fma_f32 v147, -v146, v145, v144
	v_cmp_ge_f32_e64 s[4:5], 0, v147
	v_add_u32_e32 v147, 1, v145
	s_nop 0
	v_cndmask_b32_e64 v146, v145, v146, s[4:5]
	v_fma_f32 v145, -v147, v145, v144
	v_cmp_lt_f32_e64 s[4:5], 0, v145
	s_nop 1
	v_cndmask_b32_e64 v145, v146, v147, s[4:5]
	v_mul_f32_e32 v146, 0x37800000, v145
	v_cndmask_b32_e32 v145, v145, v146, vcc
	v_cmp_class_f32_e32 vcc, v144, v238
	s_nop 1
	v_cndmask_b32_e32 v144, v145, v144, vcc
	v_div_scale_f32 v145, s[4:5], v144, v144, 1.0
	v_rcp_f32_e32 v146, v145
	s_add_u32 s5, s62, s47
	s_addc_u32 s4, 0, s52
	s_addk_i32 s10, 0x4000
	v_fma_f32 v147, -v145, v146, 1.0
	v_fmac_f32_e32 v146, v147, v146
	v_div_scale_f32 v147, vcc, 1.0, v144, 1.0
	v_mul_f32_e32 v148, v147, v146
	v_fma_f32 v149, -v145, v148, v147
	v_fmac_f32_e32 v148, v149, v146
	v_fma_f32 v145, -v145, v148, v147
	v_div_fmas_f32 v145, v145, v146, v148
	v_div_fixup_f32 v144, v145, v144, 1.0
	v_lshrrev_b32_e32 v145, 3, v137
	v_and_b32_e32 v145, 4, v145
	v_lshlrev_b32_e32 v146, 1, v137
	v_and_b32_e32 v146, 62, v146
	v_mul_u32_u24_e32 v145, 0x110, v145
	v_add3_u32 v145, s46, v146, v145
	v_bfe_u32 v146, v112, 16, 1
	v_add3_u32 v112, v112, v146, s12
	ds_write_b16_d16_hi v145, v112
	v_bfe_u32 v112, v96, 16, 1
	v_add3_u32 v96, v96, v112, s12
	ds_write_b16_d16_hi v145, v96 offset:64
	v_bfe_u32 v96, v80, 16, 1
	v_add3_u32 v80, v80, v96, s12
	ds_write_b16_d16_hi v145, v80 offset:128
	v_bfe_u32 v80, v64, 16, 1
	v_add3_u32 v64, v64, v80, s12
	ds_write_b16_d16_hi v145, v64 offset:192
	v_mul_f32_e32 v64, v113, v129
	v_bfe_u32 v80, v64, 16, 1
	v_add3_u32 v64, v64, v80, s12
	ds_write_b16_d16_hi v145, v64 offset:272
	v_mul_f32_e32 v64, v97, v129
	v_bfe_u32 v80, v64, 16, 1
	v_add3_u32 v64, v64, v80, s12
	ds_write_b16_d16_hi v145, v64 offset:336
	v_mul_f32_e32 v64, v81, v129
	v_bfe_u32 v80, v64, 16, 1
	v_add3_u32 v64, v64, v80, s12
	ds_write_b16_d16_hi v145, v64 offset:400
	v_mul_f32_e32 v64, v65, v129
	v_bfe_u32 v65, v64, 16, 1
	v_add3_u32 v64, v64, v65, s12
	ds_write_b16_d16_hi v145, v64 offset:464
	v_mul_f32_e32 v64, v114, v130
	v_bfe_u32 v65, v64, 16, 1
	v_add3_u32 v64, v64, v65, s12
	ds_write_b16_d16_hi v145, v64 offset:544
	v_mul_f32_e32 v64, v98, v130
	v_bfe_u32 v65, v64, 16, 1
	v_add3_u32 v64, v64, v65, s12
	ds_write_b16_d16_hi v145, v64 offset:608
	v_mul_f32_e32 v64, v82, v130
	v_bfe_u32 v65, v64, 16, 1
	v_add3_u32 v64, v64, v65, s12
	ds_write_b16_d16_hi v145, v64 offset:672
	v_mul_f32_e32 v64, v66, v130
	v_bfe_u32 v65, v64, 16, 1
	v_add3_u32 v64, v64, v65, s12
	ds_write_b16_d16_hi v145, v64 offset:736
	v_mul_f32_e32 v64, v115, v131
	v_bfe_u32 v65, v64, 16, 1
	v_add3_u32 v64, v64, v65, s12
	ds_write_b16_d16_hi v145, v64 offset:816
; #define LAS __attribute__((address_space(3)))
; DI unsigned f2bf(float f) { unsigned u = __builtin_bit_cast(unsigned, f); return (u + 0x7fffu + ((u >> 16) & 1u)) >> 16; }
; DI void ret_unit(LAS unsigned char* lds, bf16_t* MX, const bf16_t* VT, bf16_t* ST, int b, int hh, int qt, float lgf, float nlgb, int wave, const int mode) {
;     ...
;     for (int hf = 0; hf < 2; ++hf) {
; #pragma unroll
;         for (int i = 0; i < 16; ++i) { const int q = (i & 3) + 8 * (i >> 2) + 4 * he;
; #pragma unroll
;             for (int d4 = 0; d4 < 4; ++d4) *(LAS bf16_t*)(T + q * 272 + (d4 * 32 + re) * 2) = (bf16_t)f2bf(z[hf * 4 + d4][i] * nrm[i]); }
;         asm volatile("s_waitcnt lgkmcnt(0)" ::: "memory");
; #pragma unroll
;         for (int k = 0; k < 8; ++k) { const int id = le + 64 * k, q = id >> 4, ch = id & 15;
;             const u32x4 ov = *(const LAS u32x4*)(T + q * 272 + ch * 16);
;             bf16_t* gp = MX + (tok0 + q0w + q) * MXW + C_RG + hh * 256 + hf * 128 + ch * 8;
	v_mul_f32_e32 v64, v99, v131
	v_bfe_u32 v65, v64, 16, 1
	v_add3_u32 v64, v64, v65, s12
	ds_write_b16_d16_hi v145, v64 offset:880
	v_mul_f32_e32 v64, v83, v131
	v_bfe_u32 v65, v64, 16, 1
	v_add3_u32 v64, v64, v65, s12
	ds_write_b16_d16_hi v145, v64 offset:944
	v_mul_f32_e32 v64, v67, v131
	v_bfe_u32 v65, v64, 16, 1
	v_add3_u32 v64, v64, v65, s12
	ds_write_b16_d16_hi v145, v64 offset:1008
	v_mul_f32_e32 v64, v116, v132
	v_bfe_u32 v65, v64, 16, 1
	v_add3_u32 v64, v64, v65, s12
	ds_write_b16_d16_hi v145, v64 offset:2176
	v_mul_f32_e32 v64, v100, v132
	v_bfe_u32 v65, v64, 16, 1
	v_add3_u32 v64, v64, v65, s12
	ds_write_b16_d16_hi v145, v64 offset:2240
	v_mul_f32_e32 v64, v84, v132
	v_bfe_u32 v65, v64, 16, 1
	v_add3_u32 v64, v64, v65, s12
	ds_write_b16_d16_hi v145, v64 offset:2304
	v_mul_f32_e32 v64, v68, v132
	v_bfe_u32 v65, v64, 16, 1
	v_add3_u32 v64, v64, v65, s12
	ds_write_b16_d16_hi v145, v64 offset:2368
	v_mul_f32_e32 v64, v117, v133
	v_bfe_u32 v65, v64, 16, 1
	v_add3_u32 v64, v64, v65, s12
	ds_write_b16_d16_hi v145, v64 offset:2448
	v_mul_f32_e32 v64, v101, v133
	v_bfe_u32 v65, v64, 16, 1
	v_add3_u32 v64, v64, v65, s12
	ds_write_b16_d16_hi v145, v64 offset:2512
	v_mul_f32_e32 v64, v85, v133
	v_bfe_u32 v65, v64, 16, 1
	v_add3_u32 v64, v64, v65, s12
	ds_write_b16_d16_hi v145, v64 offset:2576
	v_mul_f32_e32 v64, v69, v133
	v_bfe_u32 v65, v64, 16, 1
	v_add3_u32 v64, v64, v65, s12
	ds_write_b16_d16_hi v145, v64 offset:2640
	v_mul_f32_e32 v64, v118, v134
	v_bfe_u32 v65, v64, 16, 1
	v_add3_u32 v64, v64, v65, s12
	ds_write_b16_d16_hi v145, v64 offset:2720
	v_mul_f32_e32 v64, v102, v134
	v_bfe_u32 v65, v64, 16, 1
	v_add3_u32 v64, v64, v65, s12
	ds_write_b16_d16_hi v145, v64 offset:2784
	v_mul_f32_e32 v64, v86, v134
	v_bfe_u32 v65, v64, 16, 1
	v_add3_u32 v64, v64, v65, s12
	ds_write_b16_d16_hi v145, v64 offset:2848
	v_mul_f32_e32 v64, v70, v134
	v_bfe_u32 v65, v64, 16, 1
	v_add3_u32 v64, v64, v65, s12
	ds_write_b16_d16_hi v145, v64 offset:2912
	v_mul_f32_e32 v64, v119, v135
	v_bfe_u32 v65, v64, 16, 1
	v_add3_u32 v64, v64, v65, s12
	ds_write_b16_d16_hi v145, v64 offset:2992
	v_mul_f32_e32 v64, v103, v135
	v_bfe_u32 v65, v64, 16, 1
	v_add3_u32 v64, v64, v65, s12
	ds_write_b16_d16_hi v145, v64 offset:3056
	v_mul_f32_e32 v64, v87, v135
	v_bfe_u32 v65, v64, 16, 1
	v_add3_u32 v64, v64, v65, s12
	ds_write_b16_d16_hi v145, v64 offset:3120
	v_mul_f32_e32 v64, v71, v135
	v_bfe_u32 v65, v64, 16, 1
	v_add3_u32 v64, v64, v65, s12
	ds_write_b16_d16_hi v145, v64 offset:3184
	v_mul_f32_e32 v64, v120, v136
	v_bfe_u32 v65, v64, 16, 1
	v_add3_u32 v64, v64, v65, s12
	ds_write_b16_d16_hi v145, v64 offset:4352
	v_mul_f32_e32 v64, v104, v136
	v_bfe_u32 v65, v64, 16, 1
	v_add3_u32 v64, v64, v65, s12
	ds_write_b16_d16_hi v145, v64 offset:4416
	v_mul_f32_e32 v64, v88, v136
	v_bfe_u32 v65, v64, 16, 1
	v_add3_u32 v64, v64, v65, s12
	ds_write_b16_d16_hi v145, v64 offset:4480
	v_mul_f32_e32 v64, v72, v136
	v_bfe_u32 v65, v64, 16, 1
	v_add3_u32 v64, v64, v65, s12
	ds_write_b16_d16_hi v145, v64 offset:4544
	v_mul_f32_e32 v64, v121, v138
	v_bfe_u32 v65, v64, 16, 1
	v_add3_u32 v64, v64, v65, s12
	ds_write_b16_d16_hi v145, v64 offset:4624
	v_mul_f32_e32 v64, v105, v138
	v_bfe_u32 v65, v64, 16, 1
	v_add3_u32 v64, v64, v65, s12
	ds_write_b16_d16_hi v145, v64 offset:4688
	v_mul_f32_e32 v64, v89, v138
	v_bfe_u32 v65, v64, 16, 1
	v_add3_u32 v64, v64, v65, s12
	ds_write_b16_d16_hi v145, v64 offset:4752
	v_mul_f32_e32 v64, v73, v138
	v_bfe_u32 v65, v64, 16, 1
	v_add3_u32 v64, v64, v65, s12
	ds_write_b16_d16_hi v145, v64 offset:4816
	v_mul_f32_e32 v64, v122, v139
	v_bfe_u32 v65, v64, 16, 1
	v_add3_u32 v64, v64, v65, s12
	ds_write_b16_d16_hi v145, v64 offset:4896
	v_mul_f32_e32 v64, v106, v139
	v_bfe_u32 v65, v64, 16, 1
	v_add3_u32 v64, v64, v65, s12
	ds_write_b16_d16_hi v145, v64 offset:4960
	v_mul_f32_e32 v64, v90, v139
	v_bfe_u32 v65, v64, 16, 1
	v_add3_u32 v64, v64, v65, s12
	ds_write_b16_d16_hi v145, v64 offset:5024
	v_mul_f32_e32 v64, v74, v139
	v_bfe_u32 v65, v64, 16, 1
	v_add3_u32 v64, v64, v65, s12
	ds_write_b16_d16_hi v145, v64 offset:5088
	v_mul_f32_e32 v64, v123, v140
	v_bfe_u32 v65, v64, 16, 1
	v_add3_u32 v64, v64, v65, s12
	ds_write_b16_d16_hi v145, v64 offset:5168
	v_mul_f32_e32 v64, v107, v140
	v_bfe_u32 v65, v64, 16, 1
	v_add3_u32 v64, v64, v65, s12
	ds_write_b16_d16_hi v145, v64 offset:5232
	v_mul_f32_e32 v64, v91, v140
	v_bfe_u32 v65, v64, 16, 1
	v_add3_u32 v64, v64, v65, s12
	ds_write_b16_d16_hi v145, v64 offset:5296
	v_mul_f32_e32 v64, v75, v140
	v_bfe_u32 v65, v64, 16, 1
	v_add3_u32 v64, v64, v65, s12
	ds_write_b16_d16_hi v145, v64 offset:5360
	v_mul_f32_e32 v64, v124, v141
	v_bfe_u32 v65, v64, 16, 1
	v_add3_u32 v64, v64, v65, s12
	ds_write_b16_d16_hi v145, v64 offset:6528
	v_mul_f32_e32 v64, v108, v141
	v_bfe_u32 v65, v64, 16, 1
	v_add3_u32 v64, v64, v65, s12
	ds_write_b16_d16_hi v145, v64 offset:6592
	v_mul_f32_e32 v64, v92, v141
	v_bfe_u32 v65, v64, 16, 1
	v_add3_u32 v64, v64, v65, s12
	ds_write_b16_d16_hi v145, v64 offset:6656
	v_mul_f32_e32 v64, v76, v141
	v_bfe_u32 v65, v64, 16, 1
	v_add3_u32 v64, v64, v65, s12
	ds_write_b16_d16_hi v145, v64 offset:6720
	v_mul_f32_e32 v64, v125, v142
	v_bfe_u32 v65, v64, 16, 1
	v_add3_u32 v64, v64, v65, s12
	ds_write_b16_d16_hi v145, v64 offset:6800
	v_mul_f32_e32 v64, v109, v142
	v_bfe_u32 v65, v64, 16, 1
	v_add3_u32 v64, v64, v65, s12
	ds_write_b16_d16_hi v145, v64 offset:6864
	v_mul_f32_e32 v64, v93, v142
	v_bfe_u32 v65, v64, 16, 1
	v_add3_u32 v64, v64, v65, s12
	ds_write_b16_d16_hi v145, v64 offset:6928
	v_mul_f32_e32 v64, v77, v142
	v_bfe_u32 v65, v64, 16, 1
	v_add3_u32 v64, v64, v65, s12
	ds_write_b16_d16_hi v145, v64 offset:6992
	v_mul_f32_e32 v64, v126, v143
	v_bfe_u32 v65, v64, 16, 1
	v_add3_u32 v64, v64, v65, s12
	ds_write_b16_d16_hi v145, v64 offset:7072
	v_mul_f32_e32 v64, v110, v143
	v_bfe_u32 v65, v64, 16, 1
	v_add3_u32 v64, v64, v65, s12
	ds_write_b16_d16_hi v145, v64 offset:7136
	v_mul_f32_e32 v64, v94, v143
	v_bfe_u32 v65, v64, 16, 1
	v_add3_u32 v64, v64, v65, s12
	ds_write_b16_d16_hi v145, v64 offset:7200
	v_mul_f32_e32 v64, v78, v143
	v_bfe_u32 v65, v64, 16, 1
	v_add3_u32 v64, v64, v65, s12
	ds_write_b16_d16_hi v145, v64 offset:7264
	v_mul_f32_e32 v64, v127, v144
	v_bfe_u32 v65, v64, 16, 1
	v_add3_u32 v64, v64, v65, s12
	ds_write_b16_d16_hi v145, v64 offset:7344
	v_mul_f32_e32 v64, v111, v144
	v_bfe_u32 v65, v64, 16, 1
	v_add3_u32 v64, v64, v65, s12
	ds_write_b16_d16_hi v145, v64 offset:7408
	v_mul_f32_e32 v64, v95, v144
	v_bfe_u32 v65, v64, 16, 1
	v_add3_u32 v64, v64, v65, s12
	v_bfe_u32 v148, v137, 4, 2
	ds_write_b16_d16_hi v145, v64 offset:7472
	v_mul_f32_e32 v64, v79, v144
	v_bfe_u32 v65, v64, 16, 1
	v_or_b32_e32 v70, s5, v148
	v_mov_b64_e32 v[68:69], s[8:9]
	v_lshlrev_b32_e32 v147, 4, v137
	v_add3_u32 v64, v64, v65, s12
	v_mad_u64_u32 v[72:73], s[14:15], v70, s50, v[68:69]
	v_and_b32_e32 v176, 0xf0, v147
	ds_write_b16_d16_hi v145, v64 offset:7536
	v_mad_i32_i24 v73, s4, v244, v73
	s_waitcnt lgkmcnt(0)
; __device__ __forceinline__ unsigned cvtpk(float lo, float hi) { f32x2_t v = {lo, hi}; bf16x2_t b = __builtin_convertvector(v, bf16x2_t); return __builtin_bit_cast(unsigned, b); }
; __device__ __forceinline__ float bf_lo(unsigned w) { return __uint_as_float(w << 16); }
; __device__ __forceinline__ float bf_hi(unsigned w) { return __uint_as_float(w & 0xffff0000u); }
; #define LAS __attribute__((address_space(3)))
; DI void ret_unit(LAS unsigned char* lds, bf16_t* MX, const bf16_t* VT, bf16_t* ST, int b, int hh, int qt, float lgf, float nlgb, int wave, const int mode) {
;     ...
;         for (int k = 0; k < 8; ++k) { const int id = le + 64 * k, q = id >> 4, ch = id & 15;
;             const u32x4 ov = *(const LAS u32x4*)(T + q * 272 + ch * 16);
;             bf16_t* gp = MX + (tok0 + q0w + q) * MXW + C_RG + hh * 256 + hf * 128 + ch * 8;
;             const u32x4 gv = *(const u32x4*)gp;
;             u32x4 w; w.x = cvtpk(bf_lo(ov.x) * bf_lo(gv.x), bf_hi(ov.x) * bf_hi(gv.x)); w.y = cvtpk(bf_lo(ov.y) * bf_lo(gv.y), bf_hi(ov.y) * bf_hi(gv.y));
;             w.z = cvtpk(bf_lo(ov.z) * bf_lo(gv.z), bf_hi(ov.z) * bf_hi(gv.z)); w.w = cvtpk(bf_lo(ov.w) * bf_lo(gv.w), bf_hi(ov.w) * bf_hi(gv.w));
;             *(u32x4*)gp = w; }
	v_lshl_add_u64 v[74:75], v[72:73], 0, v[176:177]
	v_mad_u64_u32 v[90:91], s[14:15], v70, s50, v[68:69]
	v_mad_i32_i24 v91, s4, v244, v91
	v_lshl_add_u64 v[90:91], v[90:91], 0, v[176:177]
	global_load_dwordx4 v[96:99], v[90:91], off offset:2048
	v_or_b32_e32 v92, 4, v70
	v_mad_u64_u32 v[90:91], s[14:15], v92, s50, v[68:69]
	v_mad_i32_i24 v91, s4, v244, v91
	v_lshl_add_u64 v[90:91], v[90:91], 0, v[176:177]
	global_load_dwordx4 v[100:103], v[90:91], off offset:2048
	v_or_b32_e32 v92, 8, v70
	v_mad_u64_u32 v[90:91], s[14:15], v92, s50, v[68:69]
	v_mad_i32_i24 v91, s4, v244, v91
	v_lshl_add_u64 v[90:91], v[90:91], 0, v[176:177]
	global_load_dwordx4 v[104:107], v[90:91], off offset:2048
	v_or_b32_e32 v92, 12, v70
	v_mad_u64_u32 v[90:91], s[14:15], v92, s50, v[68:69]
	v_mad_i32_i24 v91, s4, v244, v91
	v_lshl_add_u64 v[90:91], v[90:91], 0, v[176:177]
	global_load_dwordx4 v[108:111], v[90:91], off offset:2048
	v_or_b32_e32 v92, 16, v70
	v_mad_u64_u32 v[90:91], s[14:15], v92, s50, v[68:69]
	v_mad_i32_i24 v91, s4, v244, v91
	v_lshl_add_u64 v[90:91], v[90:91], 0, v[176:177]
	global_load_dwordx4 v[112:115], v[90:91], off offset:2048
	v_or_b32_e32 v92, 20, v70
	v_mad_u64_u32 v[90:91], s[14:15], v92, s50, v[68:69]
	v_mad_i32_i24 v91, s4, v244, v91
	v_lshl_add_u64 v[90:91], v[90:91], 0, v[176:177]
	global_load_dwordx4 v[116:119], v[90:91], off offset:2048
	v_or_b32_e32 v92, 24, v70
	v_mad_u64_u32 v[90:91], s[14:15], v92, s50, v[68:69]
	v_mad_i32_i24 v91, s4, v244, v91
	v_lshl_add_u64 v[90:91], v[90:91], 0, v[176:177]
	global_load_dwordx4 v[120:123], v[90:91], off offset:2048
	v_or_b32_e32 v92, 28, v70
	v_mad_u64_u32 v[90:91], s[14:15], v92, s50, v[68:69]
	v_mad_i32_i24 v91, s4, v244, v91
	v_lshl_add_u64 v[90:91], v[90:91], 0, v[176:177]
	global_load_dwordx4 v[124:127], v[90:91], off offset:2048
	v_add_u32_e32 v147, s46, v176
	v_mad_u32_u24 v137, v148, s11, v147
	ds_read_b128 v[64:67], v137
	v_or_b32_e32 v71, 4, v148
	v_mad_u32_u24 v88, v71, s11, v147
	v_or_b32_e32 v71, s5, v71
	s_waitcnt lgkmcnt(0)
	v_lshlrev_b32_e32 v72, 16, v64
	v_and_b32_e32 v73, 0xffff0000, v64
	s_waitcnt vmcnt(7)
	v_mov_b32_e32 v76, v96
	v_mov_b32_e32 v77, v97
	v_mov_b32_e32 v78, v98
	v_mov_b32_e32 v79, v99
	v_lshlrev_b32_e32 v80, 16, v76
	v_and_b32_e32 v81, 0xffff0000, v76
	v_pk_mul_f32 v[72:73], v[72:73], v[80:81]
	v_lshlrev_b32_e32 v76, 16, v77
	v_cvt_pk_bf16_f32 v64, v72, v73
	v_lshlrev_b32_e32 v72, 16, v65
	v_and_b32_e32 v73, 0xffff0000, v65
	v_and_b32_e32 v77, 0xffff0000, v77
	v_pk_mul_f32 v[72:73], v[72:73], v[76:77]
	v_lshlrev_b32_e32 v76, 16, v78
	v_cvt_pk_bf16_f32 v65, v72, v73
	v_lshlrev_b32_e32 v72, 16, v66
	v_and_b32_e32 v73, 0xffff0000, v66
	v_and_b32_e32 v77, 0xffff0000, v78
	v_pk_mul_f32 v[72:73], v[72:73], v[76:77]
	v_lshlrev_b32_e32 v76, 16, v79
	v_cvt_pk_bf16_f32 v66, v72, v73
	v_lshlrev_b32_e32 v72, 16, v67
	v_and_b32_e32 v73, 0xffff0000, v67
	v_and_b32_e32 v77, 0xffff0000, v79
	v_pk_mul_f32 v[72:73], v[72:73], v[76:77]
	s_nop 0
	v_cvt_pk_bf16_f32 v67, v72, v73
	v_mad_u64_u32 v[72:73], s[14:15], v71, s50, v[68:69]
	v_mad_i32_i24 v73, s4, v244, v73
	v_lshl_add_u64 v[76:77], v[72:73], 0, v[176:177]
	v_or_b32_e32 v71, 8, v70
	flat_store_dwordx4 v[74:75], v[64:67] offset:2048
	ds_read_b128 v[64:67], v88
	s_waitcnt lgkmcnt(0)
	v_lshlrev_b32_e32 v72, 16, v64
	v_and_b32_e32 v73, 0xffff0000, v64
	s_waitcnt vmcnt(7)
	v_mov_b32_e32 v78, v100
	v_mov_b32_e32 v79, v101
	v_mov_b32_e32 v80, v102
	v_mov_b32_e32 v81, v103
	v_lshlrev_b32_e32 v82, 16, v78
	v_and_b32_e32 v83, 0xffff0000, v78
	v_pk_mul_f32 v[72:73], v[72:73], v[82:83]
	v_lshlrev_b32_e32 v78, 16, v79
	v_cvt_pk_bf16_f32 v64, v72, v73
	v_lshlrev_b32_e32 v72, 16, v65
	v_and_b32_e32 v73, 0xffff0000, v65
	v_and_b32_e32 v79, 0xffff0000, v79
	v_pk_mul_f32 v[72:73], v[72:73], v[78:79]
	v_lshlrev_b32_e32 v78, 16, v80
	v_cvt_pk_bf16_f32 v65, v72, v73
	v_lshlrev_b32_e32 v72, 16, v66
	v_and_b32_e32 v73, 0xffff0000, v66
	v_and_b32_e32 v79, 0xffff0000, v80
	v_pk_mul_f32 v[72:73], v[72:73], v[78:79]
	v_lshlrev_b32_e32 v78, 16, v81
	v_cvt_pk_bf16_f32 v66, v72, v73
	v_lshlrev_b32_e32 v72, 16, v67
	v_and_b32_e32 v73, 0xffff0000, v67
	v_and_b32_e32 v79, 0xffff0000, v81
	v_pk_mul_f32 v[72:73], v[72:73], v[78:79]
	s_nop 0
	v_cvt_pk_bf16_f32 v67, v72, v73
	v_mad_u64_u32 v[72:73], s[14:15], v71, s50, v[68:69]
	v_mad_i32_i24 v73, s4, v244, v73
	v_lshl_add_u64 v[78:79], v[72:73], 0, v[176:177]
	v_or_b32_e32 v71, 12, v70
	flat_store_dwordx4 v[76:77], v[64:67] offset:2048
	ds_read_b128 v[64:67], v88 offset:1088
	s_waitcnt lgkmcnt(0)
	v_lshlrev_b32_e32 v72, 16, v64
	v_and_b32_e32 v73, 0xffff0000, v64
	s_waitcnt vmcnt(7)
	v_mov_b32_e32 v80, v104
	v_mov_b32_e32 v81, v105
	v_mov_b32_e32 v82, v106
	v_mov_b32_e32 v83, v107
	v_lshlrev_b32_e32 v84, 16, v80
	v_and_b32_e32 v85, 0xffff0000, v80
	v_pk_mul_f32 v[72:73], v[72:73], v[84:85]
	v_lshlrev_b32_e32 v80, 16, v81
	v_cvt_pk_bf16_f32 v64, v72, v73
	v_lshlrev_b32_e32 v72, 16, v65
	v_and_b32_e32 v73, 0xffff0000, v65
	v_and_b32_e32 v81, 0xffff0000, v81
	v_pk_mul_f32 v[72:73], v[72:73], v[80:81]
	v_lshlrev_b32_e32 v80, 16, v82
	v_cvt_pk_bf16_f32 v65, v72, v73
	v_lshlrev_b32_e32 v72, 16, v66
	v_and_b32_e32 v73, 0xffff0000, v66
	v_and_b32_e32 v81, 0xffff0000, v82
	v_pk_mul_f32 v[72:73], v[72:73], v[80:81]
	v_lshlrev_b32_e32 v80, 16, v83
	v_cvt_pk_bf16_f32 v66, v72, v73
	v_lshlrev_b32_e32 v72, 16, v67
	v_and_b32_e32 v73, 0xffff0000, v67
	v_and_b32_e32 v81, 0xffff0000, v83
	v_pk_mul_f32 v[72:73], v[72:73], v[80:81]
	s_nop 0
	v_cvt_pk_bf16_f32 v67, v72, v73
	v_mad_u64_u32 v[72:73], s[14:15], v71, s50, v[68:69]
	v_mad_i32_i24 v73, s4, v244, v73
	v_lshl_add_u64 v[82:83], v[72:73], 0, v[176:177]
	v_or_b32_e32 v71, 16, v70
	flat_store_dwordx4 v[78:79], v[64:67] offset:2048
	ds_read_b128 v[64:67], v88 offset:2176
	s_waitcnt lgkmcnt(0)
; __device__ __forceinline__ unsigned cvtpk(float lo, float hi) { f32x2_t v = {lo, hi}; bf16x2_t b = __builtin_convertvector(v, bf16x2_t); return __builtin_bit_cast(unsigned, b); }
; __device__ __forceinline__ float bf_lo(unsigned w) { return __uint_as_float(w << 16); }
; __device__ __forceinline__ float bf_hi(unsigned w) { return __uint_as_float(w & 0xffff0000u); }
; #define LAS __attribute__((address_space(3)))
; DI void ret_unit(LAS unsigned char* lds, bf16_t* MX, const bf16_t* VT, bf16_t* ST, int b, int hh, int qt, float lgf, float nlgb, int wave, const int mode) {
;     ...
;         for (int k = 0; k < 8; ++k) { const int id = le + 64 * k, q = id >> 4, ch = id & 15;
;             const u32x4 ov = *(const LAS u32x4*)(T + q * 272 + ch * 16);
;             bf16_t* gp = MX + (tok0 + q0w + q) * MXW + C_RG + hh * 256 + hf * 128 + ch * 8;
;             const u32x4 gv = *(const u32x4*)gp;
;             u32x4 w; w.x = cvtpk(bf_lo(ov.x) * bf_lo(gv.x), bf_hi(ov.x) * bf_hi(gv.x)); w.y = cvtpk(bf_lo(ov.y) * bf_lo(gv.y), bf_hi(ov.y) * bf_hi(gv.y));
;             w.z = cvtpk(bf_lo(ov.z) * bf_lo(gv.z), bf_hi(ov.z) * bf_hi(gv.z)); w.w = cvtpk(bf_lo(ov.w) * bf_lo(gv.w), bf_hi(ov.w) * bf_hi(gv.w));
;             *(u32x4*)gp = w; }
	v_lshlrev_b32_e32 v72, 16, v64
	v_and_b32_e32 v73, 0xffff0000, v64
	s_waitcnt vmcnt(7)
	v_mov_b32_e32 v84, v108
	v_mov_b32_e32 v85, v109
	v_mov_b32_e32 v86, v110
	v_mov_b32_e32 v87, v111
	v_lshlrev_b32_e32 v80, 16, v84
	v_and_b32_e32 v81, 0xffff0000, v84
	v_pk_mul_f32 v[72:73], v[72:73], v[80:81]
	v_lshlrev_b32_e32 v80, 16, v85
	v_cvt_pk_bf16_f32 v64, v72, v73
	v_lshlrev_b32_e32 v72, 16, v65
	v_and_b32_e32 v73, 0xffff0000, v65
	v_and_b32_e32 v81, 0xffff0000, v85
	v_pk_mul_f32 v[72:73], v[72:73], v[80:81]
	v_lshlrev_b32_e32 v80, 16, v86
	v_cvt_pk_bf16_f32 v65, v72, v73
	v_lshlrev_b32_e32 v72, 16, v66
	v_and_b32_e32 v73, 0xffff0000, v66
	v_and_b32_e32 v81, 0xffff0000, v86
	v_pk_mul_f32 v[72:73], v[72:73], v[80:81]
	v_lshlrev_b32_e32 v80, 16, v87
	v_cvt_pk_bf16_f32 v66, v72, v73
	v_lshlrev_b32_e32 v72, 16, v67
	v_and_b32_e32 v73, 0xffff0000, v67
	v_and_b32_e32 v81, 0xffff0000, v87
	v_pk_mul_f32 v[72:73], v[72:73], v[80:81]
	s_nop 0
	v_cvt_pk_bf16_f32 v67, v72, v73
	v_mad_u64_u32 v[72:73], s[14:15], v71, s50, v[68:69]
	v_mad_i32_i24 v73, s4, v244, v73
	v_lshl_add_u64 v[84:85], v[72:73], 0, v[176:177]
	v_or_b32_e32 v71, 20, v70
	flat_store_dwordx4 v[82:83], v[64:67] offset:2048
	ds_read_b128 v[64:67], v88 offset:3264
	s_waitcnt lgkmcnt(0)
	v_lshlrev_b32_e32 v72, 16, v64
	v_and_b32_e32 v73, 0xffff0000, v64
	s_waitcnt vmcnt(7)
	v_mov_b32_e32 v90, v112
	v_mov_b32_e32 v91, v113
	v_mov_b32_e32 v92, v114
	v_mov_b32_e32 v93, v115
	v_lshlrev_b32_e32 v80, 16, v90
	v_and_b32_e32 v81, 0xffff0000, v90
	v_pk_mul_f32 v[72:73], v[72:73], v[80:81]
	v_lshlrev_b32_e32 v80, 16, v91
	v_cvt_pk_bf16_f32 v64, v72, v73
	v_lshlrev_b32_e32 v72, 16, v65
	v_and_b32_e32 v73, 0xffff0000, v65
	v_and_b32_e32 v81, 0xffff0000, v91
	v_pk_mul_f32 v[72:73], v[72:73], v[80:81]
	v_lshlrev_b32_e32 v80, 16, v92
	v_cvt_pk_bf16_f32 v65, v72, v73
	v_lshlrev_b32_e32 v72, 16, v66
	v_and_b32_e32 v73, 0xffff0000, v66
	v_and_b32_e32 v81, 0xffff0000, v92
	v_pk_mul_f32 v[72:73], v[72:73], v[80:81]
	v_lshlrev_b32_e32 v80, 16, v93
	v_cvt_pk_bf16_f32 v66, v72, v73
	v_lshlrev_b32_e32 v72, 16, v67
	v_and_b32_e32 v73, 0xffff0000, v67
	v_and_b32_e32 v81, 0xffff0000, v93
	v_pk_mul_f32 v[72:73], v[72:73], v[80:81]
	s_nop 0
	v_cvt_pk_bf16_f32 v67, v72, v73
	v_mad_u64_u32 v[72:73], s[14:15], v71, s50, v[68:69]
	v_mad_i32_i24 v73, s4, v244, v73
	v_lshl_add_u64 v[86:87], v[72:73], 0, v[176:177]
	v_or_b32_e32 v71, 24, v70
	flat_store_dwordx4 v[84:85], v[64:67] offset:2048
	ds_read_b128 v[64:67], v88 offset:4352
	v_or_b32_e32 v70, 28, v70
	s_waitcnt lgkmcnt(0)
	v_lshlrev_b32_e32 v72, 16, v64
	v_and_b32_e32 v73, 0xffff0000, v64
	s_waitcnt vmcnt(7)
	v_mov_b32_e32 v90, v116
	v_mov_b32_e32 v91, v117
	v_mov_b32_e32 v92, v118
	v_mov_b32_e32 v93, v119
	v_lshlrev_b32_e32 v80, 16, v90
	v_and_b32_e32 v81, 0xffff0000, v90
	v_pk_mul_f32 v[72:73], v[72:73], v[80:81]
	v_lshlrev_b32_e32 v80, 16, v91
	v_cvt_pk_bf16_f32 v64, v72, v73
	v_lshlrev_b32_e32 v72, 16, v65
	v_and_b32_e32 v73, 0xffff0000, v65
	v_and_b32_e32 v81, 0xffff0000, v91
	v_pk_mul_f32 v[72:73], v[72:73], v[80:81]
	v_lshlrev_b32_e32 v80, 16, v92
	v_cvt_pk_bf16_f32 v65, v72, v73
	v_lshlrev_b32_e32 v72, 16, v66
	v_and_b32_e32 v73, 0xffff0000, v66
	v_and_b32_e32 v81, 0xffff0000, v92
	v_pk_mul_f32 v[72:73], v[72:73], v[80:81]
	v_lshlrev_b32_e32 v80, 16, v93
	v_cvt_pk_bf16_f32 v66, v72, v73
	v_lshlrev_b32_e32 v72, 16, v67
	v_and_b32_e32 v73, 0xffff0000, v67
	v_and_b32_e32 v81, 0xffff0000, v93
	v_pk_mul_f32 v[72:73], v[72:73], v[80:81]
	s_nop 0
	v_cvt_pk_bf16_f32 v67, v72, v73
	v_mad_u64_u32 v[72:73], s[14:15], v71, s50, v[68:69]
	v_mad_i32_i24 v73, s4, v244, v73
	v_lshl_add_u64 v[80:81], v[72:73], 0, v[176:177]
	v_mad_u64_u32 v[68:69], s[14:15], v70, s50, v[68:69]
	flat_store_dwordx4 v[86:87], v[64:67] offset:2048
	ds_read_b128 v[64:67], v88 offset:5440
	v_mad_i32_i24 v69, s4, v244, v69
	s_add_i32 s4, s72, 0x100
	s_cmpk_gt_u32 s72, 0x2ff
	s_mov_b32 s72, s4
	s_waitcnt lgkmcnt(0)
	v_lshlrev_b32_e32 v72, 16, v64
	v_and_b32_e32 v73, 0xffff0000, v64
	s_waitcnt vmcnt(7)
	v_mov_b32_e32 v90, v120
	v_mov_b32_e32 v91, v121
	v_mov_b32_e32 v92, v122
	v_mov_b32_e32 v93, v123
	v_lshlrev_b32_e32 v94, 16, v90
	v_and_b32_e32 v95, 0xffff0000, v90
	v_pk_mul_f32 v[72:73], v[72:73], v[94:95]
	v_lshlrev_b32_e32 v90, 16, v91
	v_cvt_pk_bf16_f32 v64, v72, v73
	v_lshlrev_b32_e32 v72, 16, v65
	v_and_b32_e32 v73, 0xffff0000, v65
	v_and_b32_e32 v91, 0xffff0000, v91
	v_pk_mul_f32 v[72:73], v[72:73], v[90:91]
	v_lshlrev_b32_e32 v90, 16, v92
	v_cvt_pk_bf16_f32 v65, v72, v73
	v_lshlrev_b32_e32 v72, 16, v66
	v_and_b32_e32 v73, 0xffff0000, v66
	v_and_b32_e32 v91, 0xffff0000, v92
	v_pk_mul_f32 v[72:73], v[72:73], v[90:91]
	v_lshlrev_b32_e32 v90, 16, v93
	v_cvt_pk_bf16_f32 v66, v72, v73
	v_lshlrev_b32_e32 v72, 16, v67
	v_and_b32_e32 v73, 0xffff0000, v67
	v_and_b32_e32 v91, 0xffff0000, v93
	v_pk_mul_f32 v[72:73], v[72:73], v[90:91]
	s_nop 0
	v_cvt_pk_bf16_f32 v67, v72, v73
	v_lshl_add_u64 v[72:73], v[68:69], 0, v[176:177]
	s_waitcnt vmcnt(6) lgkmcnt(0)
	v_mov_b32_e32 v68, v124
	v_mov_b32_e32 v69, v125
	v_mov_b32_e32 v70, v126
	v_mov_b32_e32 v71, v127
	v_lshlrev_b32_e32 v92, 16, v68
	flat_store_dwordx4 v[80:81], v[64:67] offset:2048
	ds_read_b128 v[64:67], v88 offset:6528
	v_and_b32_e32 v93, 0xffff0000, v68
	v_lshlrev_b32_e32 v68, 16, v69
	v_and_b32_e32 v69, 0xffff0000, v69
	s_waitcnt lgkmcnt(0)
; __device__ __forceinline__ unsigned cvtpk(float lo, float hi) { f32x2_t v = {lo, hi}; bf16x2_t b = __builtin_convertvector(v, bf16x2_t); return __builtin_bit_cast(unsigned, b); }
; __device__ __forceinline__ float bf_lo(unsigned w) { return __uint_as_float(w << 16); }
; __device__ __forceinline__ float bf_hi(unsigned w) { return __uint_as_float(w & 0xffff0000u); }
; #define LAS __attribute__((address_space(3)))
; DI unsigned f2bf(float f) { unsigned u = __builtin_bit_cast(unsigned, f); return (u + 0x7fffu + ((u >> 16) & 1u)) >> 16; }
; DI void ret_unit(LAS unsigned char* lds, bf16_t* MX, const bf16_t* VT, bf16_t* ST, int b, int hh, int qt, float lgf, float nlgb, int wave, const int mode) {
;     ...
;     for (int hf = 0; hf < 2; ++hf) {
; #pragma unroll
;         for (int i = 0; i < 16; ++i) { const int q = (i & 3) + 8 * (i >> 2) + 4 * he;
; #pragma unroll
;             for (int d4 = 0; d4 < 4; ++d4) *(LAS bf16_t*)(T + q * 272 + (d4 * 32 + re) * 2) = (bf16_t)f2bf(z[hf * 4 + d4][i] * nrm[i]); }
;         asm volatile("s_waitcnt lgkmcnt(0)" ::: "memory");
; #pragma unroll
;         for (int k = 0; k < 8; ++k) { const int id = le + 64 * k, q = id >> 4, ch = id & 15;
;             const u32x4 ov = *(const LAS u32x4*)(T + q * 272 + ch * 16);
;             bf16_t* gp = MX + (tok0 + q0w + q) * MXW + C_RG + hh * 256 + hf * 128 + ch * 8;
;             const u32x4 gv = *(const u32x4*)gp;
;             u32x4 w; w.x = cvtpk(bf_lo(ov.x) * bf_lo(gv.x), bf_hi(ov.x) * bf_hi(gv.x)); w.y = cvtpk(bf_lo(ov.y) * bf_lo(gv.y), bf_hi(ov.y) * bf_hi(gv.y));
;             w.z = cvtpk(bf_lo(ov.z) * bf_lo(gv.z), bf_hi(ov.z) * bf_hi(gv.z)); w.w = cvtpk(bf_lo(ov.w) * bf_lo(gv.w), bf_hi(ov.w) * bf_hi(gv.w));
;             *(u32x4*)gp = w; }
	v_lshlrev_b32_e32 v90, 16, v64
	v_and_b32_e32 v91, 0xffff0000, v64
	v_pk_mul_f32 v[90:91], v[90:91], v[92:93]
	s_nop 0
	v_cvt_pk_bf16_f32 v64, v90, v91
	v_lshlrev_b32_e32 v90, 16, v65
	v_and_b32_e32 v91, 0xffff0000, v65
	v_pk_mul_f32 v[68:69], v[90:91], v[68:69]
	v_lshlrev_b32_e32 v90, 16, v70
	v_cvt_pk_bf16_f32 v65, v68, v69
	v_lshlrev_b32_e32 v68, 16, v66
	v_and_b32_e32 v69, 0xffff0000, v66
	v_and_b32_e32 v91, 0xffff0000, v70
	v_pk_mul_f32 v[68:69], v[68:69], v[90:91]
	v_lshlrev_b32_e32 v70, 16, v71
	v_cvt_pk_bf16_f32 v66, v68, v69
	v_lshlrev_b32_e32 v68, 16, v67
	v_and_b32_e32 v69, 0xffff0000, v67
	v_and_b32_e32 v71, 0xffff0000, v71
	v_pk_mul_f32 v[68:69], v[68:69], v[70:71]
	s_nop 0
	v_cvt_pk_bf16_f32 v67, v68, v69
	flat_store_dwordx4 v[72:73], v[64:67] offset:2048
	s_waitcnt lgkmcnt(0)
	s_nop 1
	v_bfe_u32 v64, v48, 16, 1
	v_add3_u32 v48, v48, v64, s12
	ds_write_b16_d16_hi v145, v48
	v_bfe_u32 v48, v32, 16, 1
	v_add3_u32 v32, v32, v48, s12
	ds_write_b16_d16_hi v145, v32 offset:64
	v_bfe_u32 v32, v16, 16, 1
	v_add3_u32 v16, v16, v32, s12
	ds_write_b16_d16_hi v145, v16 offset:128
	v_bfe_u32 v16, v0, 16, 1
	v_add3_u32 v0, v0, v16, s12
	ds_write_b16_d16_hi v145, v0 offset:192
	v_mul_f32_e32 v0, v49, v129
	v_bfe_u32 v16, v0, 16, 1
	v_add3_u32 v0, v0, v16, s12
	ds_write_b16_d16_hi v145, v0 offset:272
	v_mul_f32_e32 v0, v33, v129
	v_bfe_u32 v16, v0, 16, 1
	v_add3_u32 v0, v0, v16, s12
	ds_write_b16_d16_hi v145, v0 offset:336
	v_mul_f32_e32 v0, v17, v129
	v_bfe_u32 v16, v0, 16, 1
	v_add3_u32 v0, v0, v16, s12
	ds_write_b16_d16_hi v145, v0 offset:400
	v_mul_f32_e32 v0, v1, v129
	v_bfe_u32 v1, v0, 16, 1
	v_add3_u32 v0, v0, v1, s12
	ds_write_b16_d16_hi v145, v0 offset:464
	v_mul_f32_e32 v0, v50, v130
	v_bfe_u32 v1, v0, 16, 1
	v_add3_u32 v0, v0, v1, s12
	ds_write_b16_d16_hi v145, v0 offset:544
	v_mul_f32_e32 v0, v34, v130
	v_bfe_u32 v1, v0, 16, 1
	v_add3_u32 v0, v0, v1, s12
	ds_write_b16_d16_hi v145, v0 offset:608
	v_mul_f32_e32 v0, v18, v130
	v_bfe_u32 v1, v0, 16, 1
	v_add3_u32 v0, v0, v1, s12
	ds_write_b16_d16_hi v145, v0 offset:672
	v_mul_f32_e32 v0, v2, v130
	v_bfe_u32 v1, v0, 16, 1
	v_add3_u32 v0, v0, v1, s12
	ds_write_b16_d16_hi v145, v0 offset:736
	v_mul_f32_e32 v0, v51, v131
	v_bfe_u32 v1, v0, 16, 1
	v_add3_u32 v0, v0, v1, s12
	ds_write_b16_d16_hi v145, v0 offset:816
	v_mul_f32_e32 v0, v35, v131
	v_bfe_u32 v1, v0, 16, 1
	v_add3_u32 v0, v0, v1, s12
	ds_write_b16_d16_hi v145, v0 offset:880
	v_mul_f32_e32 v0, v19, v131
	v_bfe_u32 v1, v0, 16, 1
	v_add3_u32 v0, v0, v1, s12
	ds_write_b16_d16_hi v145, v0 offset:944
	v_mul_f32_e32 v0, v3, v131
	v_bfe_u32 v1, v0, 16, 1
	v_add3_u32 v0, v0, v1, s12
	ds_write_b16_d16_hi v145, v0 offset:1008
	v_mul_f32_e32 v0, v52, v132
	v_bfe_u32 v1, v0, 16, 1
	v_add3_u32 v0, v0, v1, s12
	ds_write_b16_d16_hi v145, v0 offset:2176
	v_mul_f32_e32 v0, v36, v132
	v_bfe_u32 v1, v0, 16, 1
	v_add3_u32 v0, v0, v1, s12
	ds_write_b16_d16_hi v145, v0 offset:2240
	v_mul_f32_e32 v0, v20, v132
	v_bfe_u32 v1, v0, 16, 1
	v_add3_u32 v0, v0, v1, s12
	ds_write_b16_d16_hi v145, v0 offset:2304
	v_mul_f32_e32 v0, v4, v132
	v_bfe_u32 v1, v0, 16, 1
	v_add3_u32 v0, v0, v1, s12
	ds_write_b16_d16_hi v145, v0 offset:2368
	v_mul_f32_e32 v0, v53, v133
	v_bfe_u32 v1, v0, 16, 1
	v_add3_u32 v0, v0, v1, s12
	ds_write_b16_d16_hi v145, v0 offset:2448
	v_mul_f32_e32 v0, v37, v133
	v_bfe_u32 v1, v0, 16, 1
	v_add3_u32 v0, v0, v1, s12
	ds_write_b16_d16_hi v145, v0 offset:2512
	v_mul_f32_e32 v0, v21, v133
	v_bfe_u32 v1, v0, 16, 1
	v_add3_u32 v0, v0, v1, s12
	ds_write_b16_d16_hi v145, v0 offset:2576
	v_mul_f32_e32 v0, v5, v133
	v_bfe_u32 v1, v0, 16, 1
	v_add3_u32 v0, v0, v1, s12
	ds_write_b16_d16_hi v145, v0 offset:2640
	v_mul_f32_e32 v0, v54, v134
	v_bfe_u32 v1, v0, 16, 1
	v_add3_u32 v0, v0, v1, s12
	ds_write_b16_d16_hi v145, v0 offset:2720
	v_mul_f32_e32 v0, v38, v134
	v_bfe_u32 v1, v0, 16, 1
	v_add3_u32 v0, v0, v1, s12
	ds_write_b16_d16_hi v145, v0 offset:2784
	v_mul_f32_e32 v0, v22, v134
	v_bfe_u32 v1, v0, 16, 1
	v_add3_u32 v0, v0, v1, s12
	ds_write_b16_d16_hi v145, v0 offset:2848
	v_mul_f32_e32 v0, v6, v134
	v_bfe_u32 v1, v0, 16, 1
	v_add3_u32 v0, v0, v1, s12
	ds_write_b16_d16_hi v145, v0 offset:2912
	v_mul_f32_e32 v0, v55, v135
	v_bfe_u32 v1, v0, 16, 1
	v_add3_u32 v0, v0, v1, s12
	ds_write_b16_d16_hi v145, v0 offset:2992
	v_mul_f32_e32 v0, v39, v135
	v_bfe_u32 v1, v0, 16, 1
	v_add3_u32 v0, v0, v1, s12
	ds_write_b16_d16_hi v145, v0 offset:3056
	v_mul_f32_e32 v0, v23, v135
	v_bfe_u32 v1, v0, 16, 1
	v_add3_u32 v0, v0, v1, s12
	ds_write_b16_d16_hi v145, v0 offset:3120
	v_mul_f32_e32 v0, v7, v135
	v_bfe_u32 v1, v0, 16, 1
	v_add3_u32 v0, v0, v1, s12
	ds_write_b16_d16_hi v145, v0 offset:3184
	v_mul_f32_e32 v0, v56, v136
	v_bfe_u32 v1, v0, 16, 1
	v_add3_u32 v0, v0, v1, s12
	ds_write_b16_d16_hi v145, v0 offset:4352
	v_mul_f32_e32 v0, v40, v136
	v_bfe_u32 v1, v0, 16, 1
	v_add3_u32 v0, v0, v1, s12
	ds_write_b16_d16_hi v145, v0 offset:4416
	v_mul_f32_e32 v0, v24, v136
	v_bfe_u32 v1, v0, 16, 1
	v_add3_u32 v0, v0, v1, s12
	ds_write_b16_d16_hi v145, v0 offset:4480
	v_mul_f32_e32 v0, v8, v136
	v_bfe_u32 v1, v0, 16, 1
	v_add3_u32 v0, v0, v1, s12
	ds_write_b16_d16_hi v145, v0 offset:4544
	v_mul_f32_e32 v0, v57, v138
	v_bfe_u32 v1, v0, 16, 1
	v_add3_u32 v0, v0, v1, s12
	ds_write_b16_d16_hi v145, v0 offset:4624
	v_mul_f32_e32 v0, v41, v138
	v_bfe_u32 v1, v0, 16, 1
	v_add3_u32 v0, v0, v1, s12
	ds_write_b16_d16_hi v145, v0 offset:4688
	v_mul_f32_e32 v0, v25, v138
	v_bfe_u32 v1, v0, 16, 1
	v_add3_u32 v0, v0, v1, s12
	ds_write_b16_d16_hi v145, v0 offset:4752
	v_mul_f32_e32 v0, v9, v138
	v_bfe_u32 v1, v0, 16, 1
	v_add3_u32 v0, v0, v1, s12
	ds_write_b16_d16_hi v145, v0 offset:4816
; __device__ __forceinline__ unsigned cvtpk(float lo, float hi) { f32x2_t v = {lo, hi}; bf16x2_t b = __builtin_convertvector(v, bf16x2_t); return __builtin_bit_cast(unsigned, b); }
; __device__ __forceinline__ float bf_lo(unsigned w) { return __uint_as_float(w << 16); }
; __device__ __forceinline__ float bf_hi(unsigned w) { return __uint_as_float(w & 0xffff0000u); }
; #define LAS __attribute__((address_space(3)))
; DI unsigned f2bf(float f) { unsigned u = __builtin_bit_cast(unsigned, f); return (u + 0x7fffu + ((u >> 16) & 1u)) >> 16; }
; DI void ret_unit(LAS unsigned char* lds, bf16_t* MX, const bf16_t* VT, bf16_t* ST, int b, int hh, int qt, float lgf, float nlgb, int wave, const int mode) {
;     ...
;     for (int hf = 0; hf < 2; ++hf) {
; #pragma unroll
;         for (int i = 0; i < 16; ++i) { const int q = (i & 3) + 8 * (i >> 2) + 4 * he;
; #pragma unroll
;             for (int d4 = 0; d4 < 4; ++d4) *(LAS bf16_t*)(T + q * 272 + (d4 * 32 + re) * 2) = (bf16_t)f2bf(z[hf * 4 + d4][i] * nrm[i]); }
;         asm volatile("s_waitcnt lgkmcnt(0)" ::: "memory");
; #pragma unroll
;         for (int k = 0; k < 8; ++k) { const int id = le + 64 * k, q = id >> 4, ch = id & 15;
;             const u32x4 ov = *(const LAS u32x4*)(T + q * 272 + ch * 16);
;             bf16_t* gp = MX + (tok0 + q0w + q) * MXW + C_RG + hh * 256 + hf * 128 + ch * 8;
;             const u32x4 gv = *(const u32x4*)gp;
;             u32x4 w; w.x = cvtpk(bf_lo(ov.x) * bf_lo(gv.x), bf_hi(ov.x) * bf_hi(gv.x)); w.y = cvtpk(bf_lo(ov.y) * bf_lo(gv.y), bf_hi(ov.y) * bf_hi(gv.y));
;             w.z = cvtpk(bf_lo(ov.z) * bf_lo(gv.z), bf_hi(ov.z) * bf_hi(gv.z)); w.w = cvtpk(bf_lo(ov.w) * bf_lo(gv.w), bf_hi(ov.w) * bf_hi(gv.w));
;             *(u32x4*)gp = w; }
	v_mul_f32_e32 v0, v58, v139
	v_bfe_u32 v1, v0, 16, 1
	v_add3_u32 v0, v0, v1, s12
	ds_write_b16_d16_hi v145, v0 offset:4896
	v_mul_f32_e32 v0, v42, v139
	v_bfe_u32 v1, v0, 16, 1
	v_add3_u32 v0, v0, v1, s12
	ds_write_b16_d16_hi v145, v0 offset:4960
	v_mul_f32_e32 v0, v26, v139
	v_bfe_u32 v1, v0, 16, 1
	v_add3_u32 v0, v0, v1, s12
	ds_write_b16_d16_hi v145, v0 offset:5024
	v_mul_f32_e32 v0, v10, v139
	v_bfe_u32 v1, v0, 16, 1
	v_add3_u32 v0, v0, v1, s12
	ds_write_b16_d16_hi v145, v0 offset:5088
	v_mul_f32_e32 v0, v59, v140
	v_bfe_u32 v1, v0, 16, 1
	v_add3_u32 v0, v0, v1, s12
	ds_write_b16_d16_hi v145, v0 offset:5168
	v_mul_f32_e32 v0, v43, v140
	v_bfe_u32 v1, v0, 16, 1
	v_add3_u32 v0, v0, v1, s12
	ds_write_b16_d16_hi v145, v0 offset:5232
	v_mul_f32_e32 v0, v27, v140
	v_bfe_u32 v1, v0, 16, 1
	v_add3_u32 v0, v0, v1, s12
	ds_write_b16_d16_hi v145, v0 offset:5296
	v_mul_f32_e32 v0, v11, v140
	v_bfe_u32 v1, v0, 16, 1
	v_add3_u32 v0, v0, v1, s12
	ds_write_b16_d16_hi v145, v0 offset:5360
	v_mul_f32_e32 v0, v60, v141
	v_bfe_u32 v1, v0, 16, 1
	v_add3_u32 v0, v0, v1, s12
	ds_write_b16_d16_hi v145, v0 offset:6528
	v_mul_f32_e32 v0, v44, v141
	v_bfe_u32 v1, v0, 16, 1
	v_add3_u32 v0, v0, v1, s12
	ds_write_b16_d16_hi v145, v0 offset:6592
	v_mul_f32_e32 v0, v28, v141
	v_bfe_u32 v1, v0, 16, 1
	v_add3_u32 v0, v0, v1, s12
	ds_write_b16_d16_hi v145, v0 offset:6656
	v_mul_f32_e32 v0, v12, v141
	v_bfe_u32 v1, v0, 16, 1
	v_add3_u32 v0, v0, v1, s12
	ds_write_b16_d16_hi v145, v0 offset:6720
	v_mul_f32_e32 v0, v61, v142
	v_bfe_u32 v1, v0, 16, 1
	v_add3_u32 v0, v0, v1, s12
	ds_write_b16_d16_hi v145, v0 offset:6800
	v_mul_f32_e32 v0, v45, v142
	v_bfe_u32 v1, v0, 16, 1
	v_add3_u32 v0, v0, v1, s12
	ds_write_b16_d16_hi v145, v0 offset:6864
	v_mul_f32_e32 v0, v29, v142
	v_bfe_u32 v1, v0, 16, 1
	v_add3_u32 v0, v0, v1, s12
	ds_write_b16_d16_hi v145, v0 offset:6928
	v_mul_f32_e32 v0, v13, v142
	v_bfe_u32 v1, v0, 16, 1
	v_add3_u32 v0, v0, v1, s12
	ds_write_b16_d16_hi v145, v0 offset:6992
	v_mul_f32_e32 v0, v62, v143
	v_bfe_u32 v1, v0, 16, 1
	v_add3_u32 v0, v0, v1, s12
	ds_write_b16_d16_hi v145, v0 offset:7072
	v_mul_f32_e32 v0, v46, v143
	v_bfe_u32 v1, v0, 16, 1
	v_add3_u32 v0, v0, v1, s12
	ds_write_b16_d16_hi v145, v0 offset:7136
	v_mul_f32_e32 v0, v30, v143
	v_bfe_u32 v1, v0, 16, 1
	v_add3_u32 v0, v0, v1, s12
	ds_write_b16_d16_hi v145, v0 offset:7200
	v_mul_f32_e32 v0, v14, v143
	v_bfe_u32 v1, v0, 16, 1
	v_add3_u32 v0, v0, v1, s12
	ds_write_b16_d16_hi v145, v0 offset:7264
	v_mul_f32_e32 v0, v63, v144
	v_bfe_u32 v1, v0, 16, 1
	v_add3_u32 v0, v0, v1, s12
	ds_write_b16_d16_hi v145, v0 offset:7344
	v_mul_f32_e32 v0, v47, v144
	v_bfe_u32 v1, v0, 16, 1
	v_add3_u32 v0, v0, v1, s12
	ds_write_b16_d16_hi v145, v0 offset:7408
	v_mul_f32_e32 v0, v31, v144
	v_bfe_u32 v1, v0, 16, 1
	v_add3_u32 v0, v0, v1, s12
	ds_write_b16_d16_hi v145, v0 offset:7472
	v_mul_f32_e32 v0, v15, v144
	v_bfe_u32 v1, v0, 16, 1
	v_add3_u32 v0, v0, v1, s12
	ds_write_b16_d16_hi v145, v0 offset:7536
	s_waitcnt lgkmcnt(0)
	global_load_dwordx4 v[12:15], v[74:75], off offset:2304
	global_load_dwordx4 v[16:19], v[76:77], off offset:2304
	global_load_dwordx4 v[20:23], v[78:79], off offset:2304
	global_load_dwordx4 v[24:27], v[82:83], off offset:2304
	global_load_dwordx4 v[28:31], v[84:85], off offset:2304
	global_load_dwordx4 v[32:35], v[86:87], off offset:2304
	global_load_dwordx4 v[36:39], v[80:81], off offset:2304
	global_load_dwordx4 v[40:43], v[72:73], off offset:2304
	ds_read_b128 v[0:3], v137
	s_waitcnt lgkmcnt(0)
	v_lshlrev_b32_e32 v8, 16, v0
	v_and_b32_e32 v9, 0xffff0000, v0
	s_waitcnt vmcnt(7)
	v_mov_b32_e32 v4, v12
	v_mov_b32_e32 v5, v13
	v_mov_b32_e32 v6, v14
	v_mov_b32_e32 v7, v15
	v_lshlrev_b32_e32 v10, 16, v4
	v_and_b32_e32 v11, 0xffff0000, v4
	v_pk_mul_f32 v[8:9], v[8:9], v[10:11]
	v_lshlrev_b32_e32 v4, 16, v5
	v_cvt_pk_bf16_f32 v0, v8, v9
	v_lshlrev_b32_e32 v8, 16, v1
	v_and_b32_e32 v9, 0xffff0000, v1
	v_and_b32_e32 v5, 0xffff0000, v5
	v_pk_mul_f32 v[4:5], v[8:9], v[4:5]
	v_lshlrev_b32_e32 v8, 16, v6
	v_cvt_pk_bf16_f32 v1, v4, v5
	v_lshlrev_b32_e32 v4, 16, v2
	v_and_b32_e32 v5, 0xffff0000, v2
	v_and_b32_e32 v9, 0xffff0000, v6
	v_pk_mul_f32 v[4:5], v[4:5], v[8:9]
	v_lshlrev_b32_e32 v6, 16, v7
	v_cvt_pk_bf16_f32 v2, v4, v5
	v_lshlrev_b32_e32 v4, 16, v3
	v_and_b32_e32 v5, 0xffff0000, v3
	v_and_b32_e32 v7, 0xffff0000, v7
	v_pk_mul_f32 v[4:5], v[4:5], v[6:7]
	s_nop 0
	v_cvt_pk_bf16_f32 v3, v4, v5
	s_waitcnt vmcnt(6) lgkmcnt(0)
	v_mov_b32_e32 v4, v16
	v_mov_b32_e32 v5, v17
	v_mov_b32_e32 v6, v18
	v_mov_b32_e32 v7, v19
	v_lshlrev_b32_e32 v10, 16, v4
	flat_store_dwordx4 v[74:75], v[0:3] offset:2304
	ds_read_b128 v[0:3], v88
	v_and_b32_e32 v11, 0xffff0000, v4
	v_lshlrev_b32_e32 v4, 16, v5
	v_and_b32_e32 v5, 0xffff0000, v5
	s_waitcnt lgkmcnt(0)
	v_lshlrev_b32_e32 v8, 16, v0
	v_and_b32_e32 v9, 0xffff0000, v0
	v_pk_mul_f32 v[8:9], v[8:9], v[10:11]
	s_nop 0
	v_cvt_pk_bf16_f32 v0, v8, v9
	v_lshlrev_b32_e32 v8, 16, v1
	v_and_b32_e32 v9, 0xffff0000, v1
	v_pk_mul_f32 v[4:5], v[8:9], v[4:5]
	v_lshlrev_b32_e32 v8, 16, v6
	v_cvt_pk_bf16_f32 v1, v4, v5
	v_lshlrev_b32_e32 v4, 16, v2
	v_and_b32_e32 v5, 0xffff0000, v2
	v_and_b32_e32 v9, 0xffff0000, v6
	v_pk_mul_f32 v[4:5], v[4:5], v[8:9]
	v_lshlrev_b32_e32 v6, 16, v7
	v_cvt_pk_bf16_f32 v2, v4, v5
	v_lshlrev_b32_e32 v4, 16, v3
	v_and_b32_e32 v5, 0xffff0000, v3
	v_and_b32_e32 v7, 0xffff0000, v7
	v_pk_mul_f32 v[4:5], v[4:5], v[6:7]
	s_nop 0
	v_cvt_pk_bf16_f32 v3, v4, v5
	s_waitcnt vmcnt(6) lgkmcnt(0)
	v_mov_b32_e32 v4, v20
	v_mov_b32_e32 v5, v21
	v_mov_b32_e32 v6, v22
	v_mov_b32_e32 v7, v23
	v_lshlrev_b32_e32 v10, 16, v4
	flat_store_dwordx4 v[76:77], v[0:3] offset:2304
	ds_read_b128 v[0:3], v88 offset:1088
	v_and_b32_e32 v11, 0xffff0000, v4
	v_lshlrev_b32_e32 v4, 16, v5
	v_and_b32_e32 v5, 0xffff0000, v5
	s_waitcnt lgkmcnt(0)
; __device__ __forceinline__ unsigned cvtpk(float lo, float hi) { f32x2_t v = {lo, hi}; bf16x2_t b = __builtin_convertvector(v, bf16x2_t); return __builtin_bit_cast(unsigned, b); }
; __device__ __forceinline__ float bf_lo(unsigned w) { return __uint_as_float(w << 16); }
; __device__ __forceinline__ float bf_hi(unsigned w) { return __uint_as_float(w & 0xffff0000u); }
; #define LAS __attribute__((address_space(3)))
; DI void ret_unit(LAS unsigned char* lds, bf16_t* MX, const bf16_t* VT, bf16_t* ST, int b, int hh, int qt, float lgf, float nlgb, int wave, const int mode) {
;     ...
;         for (int k = 0; k < 8; ++k) { const int id = le + 64 * k, q = id >> 4, ch = id & 15;
;             const u32x4 ov = *(const LAS u32x4*)(T + q * 272 + ch * 16);
;             bf16_t* gp = MX + (tok0 + q0w + q) * MXW + C_RG + hh * 256 + hf * 128 + ch * 8;
;             const u32x4 gv = *(const u32x4*)gp;
;             u32x4 w; w.x = cvtpk(bf_lo(ov.x) * bf_lo(gv.x), bf_hi(ov.x) * bf_hi(gv.x)); w.y = cvtpk(bf_lo(ov.y) * bf_lo(gv.y), bf_hi(ov.y) * bf_hi(gv.y));
;             w.z = cvtpk(bf_lo(ov.z) * bf_lo(gv.z), bf_hi(ov.z) * bf_hi(gv.z)); w.w = cvtpk(bf_lo(ov.w) * bf_lo(gv.w), bf_hi(ov.w) * bf_hi(gv.w));
;             *(u32x4*)gp = w; }
;         asm volatile("s_waitcnt lgkmcnt(0)" ::: "memory");
;     }
	v_lshlrev_b32_e32 v8, 16, v0
	v_and_b32_e32 v9, 0xffff0000, v0
	v_pk_mul_f32 v[8:9], v[8:9], v[10:11]
	s_nop 0
	v_cvt_pk_bf16_f32 v0, v8, v9
	v_lshlrev_b32_e32 v8, 16, v1
	v_and_b32_e32 v9, 0xffff0000, v1
	v_pk_mul_f32 v[4:5], v[8:9], v[4:5]
	v_lshlrev_b32_e32 v8, 16, v6
	v_cvt_pk_bf16_f32 v1, v4, v5
	v_lshlrev_b32_e32 v4, 16, v2
	v_and_b32_e32 v5, 0xffff0000, v2
	v_and_b32_e32 v9, 0xffff0000, v6
	v_pk_mul_f32 v[4:5], v[4:5], v[8:9]
	v_lshlrev_b32_e32 v6, 16, v7
	v_cvt_pk_bf16_f32 v2, v4, v5
	v_lshlrev_b32_e32 v4, 16, v3
	v_and_b32_e32 v5, 0xffff0000, v3
	v_and_b32_e32 v7, 0xffff0000, v7
	v_pk_mul_f32 v[4:5], v[4:5], v[6:7]
	s_nop 0
	v_cvt_pk_bf16_f32 v3, v4, v5
	s_waitcnt vmcnt(6) lgkmcnt(0)
	v_mov_b32_e32 v4, v24
	v_mov_b32_e32 v5, v25
	v_mov_b32_e32 v6, v26
	v_mov_b32_e32 v7, v27
	v_lshlrev_b32_e32 v10, 16, v4
	flat_store_dwordx4 v[78:79], v[0:3] offset:2304
	ds_read_b128 v[0:3], v88 offset:2176
	v_and_b32_e32 v11, 0xffff0000, v4
	v_lshlrev_b32_e32 v4, 16, v5
	v_and_b32_e32 v5, 0xffff0000, v5
	s_waitcnt lgkmcnt(0)
	v_lshlrev_b32_e32 v8, 16, v0
	v_and_b32_e32 v9, 0xffff0000, v0
	v_pk_mul_f32 v[8:9], v[8:9], v[10:11]
	s_nop 0
	v_cvt_pk_bf16_f32 v0, v8, v9
	v_lshlrev_b32_e32 v8, 16, v1
	v_and_b32_e32 v9, 0xffff0000, v1
	v_pk_mul_f32 v[4:5], v[8:9], v[4:5]
	v_lshlrev_b32_e32 v8, 16, v6
	v_cvt_pk_bf16_f32 v1, v4, v5
	v_lshlrev_b32_e32 v4, 16, v2
	v_and_b32_e32 v5, 0xffff0000, v2
	v_and_b32_e32 v9, 0xffff0000, v6
	v_pk_mul_f32 v[4:5], v[4:5], v[8:9]
	v_lshlrev_b32_e32 v6, 16, v7
	v_cvt_pk_bf16_f32 v2, v4, v5
	v_lshlrev_b32_e32 v4, 16, v3
	v_and_b32_e32 v5, 0xffff0000, v3
	v_and_b32_e32 v7, 0xffff0000, v7
	v_pk_mul_f32 v[4:5], v[4:5], v[6:7]
	s_nop 0
	v_cvt_pk_bf16_f32 v3, v4, v5
	s_waitcnt vmcnt(6) lgkmcnt(0)
	v_mov_b32_e32 v4, v28
	v_mov_b32_e32 v5, v29
	v_mov_b32_e32 v6, v30
	v_mov_b32_e32 v7, v31
	v_lshlrev_b32_e32 v10, 16, v4
	flat_store_dwordx4 v[82:83], v[0:3] offset:2304
	ds_read_b128 v[0:3], v88 offset:3264
	v_and_b32_e32 v11, 0xffff0000, v4
	v_lshlrev_b32_e32 v4, 16, v5
	v_and_b32_e32 v5, 0xffff0000, v5
	s_waitcnt lgkmcnt(0)
	v_lshlrev_b32_e32 v8, 16, v0
	v_and_b32_e32 v9, 0xffff0000, v0
	v_pk_mul_f32 v[8:9], v[8:9], v[10:11]
	s_nop 0
	v_cvt_pk_bf16_f32 v0, v8, v9
	v_lshlrev_b32_e32 v8, 16, v1
	v_and_b32_e32 v9, 0xffff0000, v1
	v_pk_mul_f32 v[4:5], v[8:9], v[4:5]
	v_lshlrev_b32_e32 v8, 16, v6
	v_cvt_pk_bf16_f32 v1, v4, v5
	v_lshlrev_b32_e32 v4, 16, v2
	v_and_b32_e32 v5, 0xffff0000, v2
	v_and_b32_e32 v9, 0xffff0000, v6
	v_pk_mul_f32 v[4:5], v[4:5], v[8:9]
	v_lshlrev_b32_e32 v6, 16, v7
	v_cvt_pk_bf16_f32 v2, v4, v5
	v_lshlrev_b32_e32 v4, 16, v3
	v_and_b32_e32 v5, 0xffff0000, v3
	v_and_b32_e32 v7, 0xffff0000, v7
	v_pk_mul_f32 v[4:5], v[4:5], v[6:7]
	s_nop 0
	v_cvt_pk_bf16_f32 v3, v4, v5
	s_waitcnt vmcnt(6) lgkmcnt(0)
	v_mov_b32_e32 v4, v32
	v_mov_b32_e32 v5, v33
	v_mov_b32_e32 v6, v34
	v_mov_b32_e32 v7, v35
	v_lshlrev_b32_e32 v10, 16, v4
	flat_store_dwordx4 v[84:85], v[0:3] offset:2304
	ds_read_b128 v[0:3], v88 offset:4352
	v_and_b32_e32 v11, 0xffff0000, v4
	v_lshlrev_b32_e32 v4, 16, v5
	v_and_b32_e32 v5, 0xffff0000, v5
	s_waitcnt lgkmcnt(0)
	v_lshlrev_b32_e32 v8, 16, v0
	v_and_b32_e32 v9, 0xffff0000, v0
	v_pk_mul_f32 v[8:9], v[8:9], v[10:11]
	s_nop 0
	v_cvt_pk_bf16_f32 v0, v8, v9
	v_lshlrev_b32_e32 v8, 16, v1
	v_and_b32_e32 v9, 0xffff0000, v1
	v_pk_mul_f32 v[4:5], v[8:9], v[4:5]
	v_lshlrev_b32_e32 v8, 16, v6
	v_cvt_pk_bf16_f32 v1, v4, v5
	v_lshlrev_b32_e32 v4, 16, v2
	v_and_b32_e32 v5, 0xffff0000, v2
	v_and_b32_e32 v9, 0xffff0000, v6
	v_pk_mul_f32 v[4:5], v[4:5], v[8:9]
	v_lshlrev_b32_e32 v6, 16, v7
	v_cvt_pk_bf16_f32 v2, v4, v5
	v_lshlrev_b32_e32 v4, 16, v3
	v_and_b32_e32 v5, 0xffff0000, v3
	v_and_b32_e32 v7, 0xffff0000, v7
	v_pk_mul_f32 v[4:5], v[4:5], v[6:7]
	s_nop 0
	v_cvt_pk_bf16_f32 v3, v4, v5
	s_waitcnt vmcnt(6) lgkmcnt(0)
	v_mov_b32_e32 v4, v36
	v_mov_b32_e32 v5, v37
	v_mov_b32_e32 v6, v38
	v_mov_b32_e32 v7, v39
	v_lshlrev_b32_e32 v10, 16, v4
	flat_store_dwordx4 v[86:87], v[0:3] offset:2304
	ds_read_b128 v[0:3], v88 offset:5440
	v_and_b32_e32 v11, 0xffff0000, v4
	v_lshlrev_b32_e32 v4, 16, v5
	v_and_b32_e32 v5, 0xffff0000, v5
	s_waitcnt lgkmcnt(0)
	v_lshlrev_b32_e32 v8, 16, v0
	v_and_b32_e32 v9, 0xffff0000, v0
	v_pk_mul_f32 v[8:9], v[8:9], v[10:11]
	s_nop 0
	v_cvt_pk_bf16_f32 v0, v8, v9
	v_lshlrev_b32_e32 v8, 16, v1
	v_and_b32_e32 v9, 0xffff0000, v1
	v_pk_mul_f32 v[4:5], v[8:9], v[4:5]
	v_lshlrev_b32_e32 v8, 16, v6
	v_cvt_pk_bf16_f32 v1, v4, v5
	v_lshlrev_b32_e32 v4, 16, v2
	v_and_b32_e32 v5, 0xffff0000, v2
	v_and_b32_e32 v9, 0xffff0000, v6
	v_pk_mul_f32 v[4:5], v[4:5], v[8:9]
	v_lshlrev_b32_e32 v6, 16, v7
	v_cvt_pk_bf16_f32 v2, v4, v5
	v_lshlrev_b32_e32 v4, 16, v3
	v_and_b32_e32 v5, 0xffff0000, v3
	v_and_b32_e32 v7, 0xffff0000, v7
	v_pk_mul_f32 v[4:5], v[4:5], v[6:7]
	s_nop 0
	v_cvt_pk_bf16_f32 v3, v4, v5
	s_waitcnt vmcnt(6) lgkmcnt(0)
	v_mov_b32_e32 v4, v40
	v_mov_b32_e32 v5, v41
	v_mov_b32_e32 v6, v42
	v_mov_b32_e32 v7, v43
	v_lshlrev_b32_e32 v10, 16, v4
	flat_store_dwordx4 v[80:81], v[0:3] offset:2304
	ds_read_b128 v[0:3], v88 offset:6528
	v_and_b32_e32 v11, 0xffff0000, v4
	v_lshlrev_b32_e32 v4, 16, v5
	v_and_b32_e32 v5, 0xffff0000, v5
	s_waitcnt lgkmcnt(0)
	v_lshlrev_b32_e32 v8, 16, v0
	v_and_b32_e32 v9, 0xffff0000, v0
	v_pk_mul_f32 v[8:9], v[8:9], v[10:11]
	s_nop 0
	v_cvt_pk_bf16_f32 v0, v8, v9
	v_lshlrev_b32_e32 v8, 16, v1
	v_and_b32_e32 v9, 0xffff0000, v1
	v_pk_mul_f32 v[4:5], v[8:9], v[4:5]
	v_lshlrev_b32_e32 v8, 16, v6
	v_cvt_pk_bf16_f32 v1, v4, v5
	v_lshlrev_b32_e32 v4, 16, v2
	v_and_b32_e32 v5, 0xffff0000, v2
	v_and_b32_e32 v9, 0xffff0000, v6
	v_pk_mul_f32 v[4:5], v[4:5], v[8:9]
	v_lshlrev_b32_e32 v6, 16, v7
	v_cvt_pk_bf16_f32 v2, v4, v5
	v_lshlrev_b32_e32 v4, 16, v3
	v_and_b32_e32 v5, 0xffff0000, v3
	v_and_b32_e32 v7, 0xffff0000, v7
	v_pk_mul_f32 v[4:5], v[4:5], v[6:7]
	s_nop 0
	v_cvt_pk_bf16_f32 v3, v4, v5
	flat_store_dwordx4 v[72:73], v[0:3] offset:2304
	s_waitcnt lgkmcnt(0)
	s_cbranch_scc1 .LBB0_181
